# prefetch LDS-DMA of the next unit spread through the gate/up epilogue's VALU stream (phases 7 and 15) instead of issued back-to-back
# baseline (speedup 1.0000x reference)
.Lpf7_p1_skip:
	ds_read_b128 v[116:119], v14
	ds_read_b128 v[120:123], v14 offset:2048
	ds_read_b128 v[124:127], v14 offset:4096
	ds_read_b128 v[128:131], v14 offset:6144
	ds_read_b128 v[132:135], v15
	ds_read_b128 v[136:139], v15 offset:2048
	ds_read_b128 v[140:143], v15 offset:4096
	ds_read_b128 v[144:147], v15 offset:6144
	v_mfma_f32_16x16x32_bf16 v[80:83], v[100:103], v[72:75], v[80:83]
	v_mfma_f32_16x16x32_bf16 v[84:87], v[104:107], v[72:75], v[84:87]
	v_mfma_f32_16x16x32_bf16 v[88:91], v[108:111], v[72:75], v[88:91]
	v_mfma_f32_16x16x32_bf16 v[22:25], v[112:115], v[72:75], v[22:25]
	v_mfma_f32_16x16x32_bf16 v[38:41], v[100:103], v[76:79], v[38:41]
	v_mfma_f32_16x16x32_bf16 v[46:49], v[104:107], v[76:79], v[46:49]
	v_mfma_f32_16x16x32_bf16 v[58:61], v[108:111], v[76:79], v[58:61]
	v_mfma_f32_16x16x32_bf16 v[50:53], v[112:115], v[76:79], v[50:53]
	v_mfma_f32_16x16x32_bf16 v[42:45], v[100:103], v[92:95], v[42:45]
	v_mfma_f32_16x16x32_bf16 v[62:65], v[104:107], v[92:95], v[62:65]
	v_mfma_f32_16x16x32_bf16 v[68:71], v[108:111], v[92:95], v[68:71]
	v_mfma_f32_16x16x32_bf16 v[54:57], v[112:115], v[92:95], v[54:57]
	v_mfma_f32_16x16x32_bf16 v[34:37], v[100:103], v[96:99], v[34:37]
	v_mfma_f32_16x16x32_bf16 v[30:33], v[104:107], v[96:99], v[30:33]
	v_mfma_f32_16x16x32_bf16 v[26:29], v[108:111], v[96:99], v[26:29]
	v_mfma_f32_16x16x32_bf16 v[18:21], v[112:115], v[96:99], v[18:21]
	s_mov_b32 m0, s63
	v_lshl_add_u64 v[72:73], v[4:5], 0, s[30:31]
	global_load_lds_dwordx4 v[72:73], off
	v_lshl_add_u64 v[72:73], v[6:7], 0, s[30:31]
	s_mov_b32 m0, s62
	s_mov_b64 s[62:63], 0x20680
	global_load_lds_dwordx4 v[72:73], off
	v_lshl_add_u64 v[72:73], v[2:3], 0, s[30:31]
	s_mov_b32 m0, s64
	s_nop 0
	global_load_lds_dwordx4 v[72:73], off
	v_lshl_add_u64 v[72:73], v[2:3], 0, s[62:63]
	s_mov_b32 m0, s65
	s_mov_b64 s[62:63], 0x40680
	global_load_lds_dwordx4 v[72:73], off
	v_lshl_add_u64 v[72:73], v[2:3], 0, s[62:63]
	s_mov_b32 m0, s66
	s_mov_b64 s[62:63], 0x60680
	global_load_lds_dwordx4 v[72:73], off
	v_lshl_add_u64 v[72:73], v[2:3], 0, s[62:63]
	s_mov_b32 m0, s67
	v_readlane_b32 s66, v196, 22
	global_load_lds_dwordx4 v[72:73], off
	ds_read_b128 v[72:75], v16
	ds_read_b128 v[76:79], v16 offset:2048
	ds_read_b128 v[92:95], v16 offset:4096
	ds_read_b128 v[96:99], v16 offset:6144
	ds_read_b128 v[100:103], v17
	ds_read_b128 v[104:107], v17 offset:2048
	ds_read_b128 v[108:111], v17 offset:4096
	ds_read_b128 v[112:115], v17 offset:6144
	v_readlane_b32 s67, v196, 23
	s_waitcnt lgkmcnt(8)
	v_mfma_f32_16x16x32_bf16 v[80:83], v[132:135], v[116:119], v[80:83]
	v_mfma_f32_16x16x32_bf16 v[84:87], v[136:139], v[116:119], v[84:87]
	v_mfma_f32_16x16x32_bf16 v[88:91], v[140:143], v[116:119], v[88:91]
	v_mfma_f32_16x16x32_bf16 v[22:25], v[144:147], v[116:119], v[22:25]
	v_mfma_f32_16x16x32_bf16 v[38:41], v[132:135], v[120:123], v[38:41]
	v_mfma_f32_16x16x32_bf16 v[46:49], v[136:139], v[120:123], v[46:49]
	v_mfma_f32_16x16x32_bf16 v[58:61], v[140:143], v[120:123], v[58:61]
	v_mfma_f32_16x16x32_bf16 v[50:53], v[144:147], v[120:123], v[50:53]
	v_mfma_f32_16x16x32_bf16 v[42:45], v[132:135], v[124:127], v[42:45]
	v_mfma_f32_16x16x32_bf16 v[62:65], v[136:139], v[124:127], v[62:65]
	v_mfma_f32_16x16x32_bf16 v[68:71], v[140:143], v[124:127], v[68:71]
	v_mfma_f32_16x16x32_bf16 v[54:57], v[144:147], v[124:127], v[54:57]
	v_mfma_f32_16x16x32_bf16 v[34:37], v[132:135], v[128:131], v[34:37]
	v_mfma_f32_16x16x32_bf16 v[30:33], v[136:139], v[128:131], v[30:33]
	v_mfma_f32_16x16x32_bf16 v[26:29], v[140:143], v[128:131], v[26:29]
	v_mfma_f32_16x16x32_bf16 v[18:21], v[144:147], v[128:131], v[18:21]
	s_waitcnt vmcnt(6) lgkmcnt(0)
	s_barrier
	ds_read_b128 v[116:119], v8
	ds_read_b128 v[120:123], v8 offset:2048
	ds_read_b128 v[124:127], v8 offset:4096
	ds_read_b128 v[128:131], v8 offset:6144
	ds_read_b128 v[132:135], v9 offset:16384
	ds_read_b128 v[136:139], v9 offset:18432
	ds_read_b128 v[140:143], v9 offset:20480
	ds_read_b128 v[144:147], v9 offset:22528
	v_mfma_f32_16x16x32_bf16 v[80:83], v[100:103], v[72:75], v[80:83]
	v_mfma_f32_16x16x32_bf16 v[84:87], v[104:107], v[72:75], v[84:87]
	v_mfma_f32_16x16x32_bf16 v[88:91], v[108:111], v[72:75], v[88:91]
	v_mfma_f32_16x16x32_bf16 v[22:25], v[112:115], v[72:75], v[22:25]
	v_mfma_f32_16x16x32_bf16 v[38:41], v[100:103], v[76:79], v[38:41]
	v_mfma_f32_16x16x32_bf16 v[46:49], v[104:107], v[76:79], v[46:49]
	v_mfma_f32_16x16x32_bf16 v[58:61], v[108:111], v[76:79], v[58:61]
	v_mfma_f32_16x16x32_bf16 v[50:53], v[112:115], v[76:79], v[50:53]
	v_mfma_f32_16x16x32_bf16 v[42:45], v[100:103], v[92:95], v[42:45]
	v_mfma_f32_16x16x32_bf16 v[62:65], v[104:107], v[92:95], v[62:65]
	v_mfma_f32_16x16x32_bf16 v[68:71], v[108:111], v[92:95], v[68:71]
	v_mfma_f32_16x16x32_bf16 v[54:57], v[112:115], v[92:95], v[54:57]
	v_mfma_f32_16x16x32_bf16 v[34:37], v[100:103], v[96:99], v[34:37]
	v_mfma_f32_16x16x32_bf16 v[30:33], v[104:107], v[96:99], v[30:33]
	v_mfma_f32_16x16x32_bf16 v[26:29], v[108:111], v[96:99], v[26:29]
	v_mfma_f32_16x16x32_bf16 v[18:21], v[112:115], v[96:99], v[18:21]
	s_mov_b32 m0, s68
	v_lshl_add_u64 v[72:73], v[4:5], 0, s[34:35]
	global_load_lds_dwordx4 v[72:73], off
	v_lshl_add_u64 v[72:73], v[6:7], 0, s[34:35]
	s_mov_b32 m0, s69
	s_mov_b64 s[62:63], 0x20700
	global_load_lds_dwordx4 v[72:73], off
	v_lshl_add_u64 v[72:73], v[2:3], 0, s[34:35]
	s_mov_b32 m0, s70
	s_nop 0
	global_load_lds_dwordx4 v[72:73], off
	v_lshl_add_u64 v[72:73], v[2:3], 0, s[62:63]
	s_mov_b32 m0, s71
	s_mov_b64 s[62:63], 0x40700
	global_load_lds_dwordx4 v[72:73], off
	v_lshl_add_u64 v[72:73], v[2:3], 0, s[62:63]
	s_mov_b32 m0, s72
	s_mov_b64 s[62:63], 0x60700
	global_load_lds_dwordx4 v[72:73], off
	v_lshl_add_u64 v[72:73], v[2:3], 0, s[62:63]
	s_mov_b32 m0, s73
	v_readlane_b32 s72, v197, 34
	global_load_lds_dwordx4 v[72:73], off
	ds_read_b128 v[72:75], v10
	ds_read_b128 v[76:79], v10 offset:2048
	ds_read_b128 v[92:95], v10 offset:4096
	ds_read_b128 v[96:99], v10 offset:6144
	ds_read_b128 v[100:103], v11 offset:16384
	ds_read_b128 v[104:107], v11 offset:18432
	ds_read_b128 v[108:111], v11 offset:20480
	ds_read_b128 v[112:115], v11 offset:22528
	v_readlane_b32 s73, v197, 35
	v_readlane_b32 s74, v197, 36
	v_readlane_b32 s75, v197, 37
	v_readlane_b32 s76, v197, 38
	v_readlane_b32 s77, v197, 39
	v_readlane_b32 s78, v197, 40
	v_readlane_b32 s79, v197, 41
	v_readlane_b32 s80, v197, 42
	v_readlane_b32 s81, v197, 43
	v_readlane_b32 s82, v197, 44
	v_readlane_b32 s83, v197, 45
	v_readlane_b32 s84, v197, 46
	v_readlane_b32 s85, v197, 47
	v_readlane_b32 s86, v197, 48
	v_readlane_b32 s87, v197, 49
	s_waitcnt lgkmcnt(8)
	v_mfma_f32_16x16x32_bf16 v[80:83], v[132:135], v[116:119], v[80:83]
	v_mfma_f32_16x16x32_bf16 v[84:87], v[136:139], v[116:119], v[84:87]
	v_mfma_f32_16x16x32_bf16 v[88:91], v[140:143], v[116:119], v[88:91]
	v_mfma_f32_16x16x32_bf16 v[22:25], v[144:147], v[116:119], v[22:25]
	v_mfma_f32_16x16x32_bf16 v[38:41], v[132:135], v[120:123], v[38:41]
	v_mfma_f32_16x16x32_bf16 v[46:49], v[136:139], v[120:123], v[46:49]
	v_mfma_f32_16x16x32_bf16 v[58:61], v[140:143], v[120:123], v[58:61]
	v_mfma_f32_16x16x32_bf16 v[50:53], v[144:147], v[120:123], v[50:53]
	v_mfma_f32_16x16x32_bf16 v[42:45], v[132:135], v[124:127], v[42:45]
	v_mfma_f32_16x16x32_bf16 v[62:65], v[136:139], v[124:127], v[62:65]
	v_mfma_f32_16x16x32_bf16 v[68:71], v[140:143], v[124:127], v[68:71]
	v_mfma_f32_16x16x32_bf16 v[54:57], v[144:147], v[124:127], v[54:57]
	v_mfma_f32_16x16x32_bf16 v[34:37], v[132:135], v[128:131], v[34:37]
	v_mfma_f32_16x16x32_bf16 v[30:33], v[136:139], v[128:131], v[30:33]
	v_mfma_f32_16x16x32_bf16 v[26:29], v[140:143], v[128:131], v[26:29]
	v_mfma_f32_16x16x32_bf16 v[18:21], v[144:147], v[128:131], v[18:21]
	s_waitcnt vmcnt(6) lgkmcnt(0)
	s_barrier
	ds_read_b128 v[116:119], v8 offset:49152
	ds_read_b128 v[120:123], v8 offset:51200
	ds_read_b128 v[124:127], v8 offset:53248
	ds_read_b128 v[128:131], v8 offset:55296
	ds_read_b128 v[132:135], v12
	ds_read_b128 v[136:139], v12 offset:2048
	ds_read_b128 v[140:143], v12 offset:4096
	ds_read_b128 v[144:147], v12 offset:6144
	v_mfma_f32_16x16x32_bf16 v[80:83], v[100:103], v[72:75], v[80:83]
	v_mfma_f32_16x16x32_bf16 v[84:87], v[104:107], v[72:75], v[84:87]
	v_mfma_f32_16x16x32_bf16 v[88:91], v[108:111], v[72:75], v[88:91]
	v_mfma_f32_16x16x32_bf16 v[22:25], v[112:115], v[72:75], v[22:25]
	v_mfma_f32_16x16x32_bf16 v[38:41], v[100:103], v[76:79], v[38:41]
	v_mfma_f32_16x16x32_bf16 v[46:49], v[104:107], v[76:79], v[46:49]
	v_mfma_f32_16x16x32_bf16 v[58:61], v[108:111], v[76:79], v[58:61]
	v_mfma_f32_16x16x32_bf16 v[50:53], v[112:115], v[76:79], v[50:53]
	v_mfma_f32_16x16x32_bf16 v[42:45], v[100:103], v[92:95], v[42:45]
	v_mfma_f32_16x16x32_bf16 v[62:65], v[104:107], v[92:95], v[62:65]
	v_mfma_f32_16x16x32_bf16 v[68:71], v[108:111], v[92:95], v[68:71]
	v_mfma_f32_16x16x32_bf16 v[54:57], v[112:115], v[92:95], v[54:57]
	v_mfma_f32_16x16x32_bf16 v[34:37], v[100:103], v[96:99], v[34:37]
	v_mfma_f32_16x16x32_bf16 v[30:33], v[104:107], v[96:99], v[30:33]
	v_mfma_f32_16x16x32_bf16 v[26:29], v[108:111], v[96:99], v[26:29]
	v_mfma_f32_16x16x32_bf16 v[18:21], v[112:115], v[96:99], v[18:21]
	s_mov_b32 m0, s61
	v_lshl_add_u64 v[4:5], v[4:5], 0, s[36:37]
	global_load_lds_dwordx4 v[4:5], off
	v_lshl_add_u64 v[4:5], v[6:7], 0, s[36:37]
	s_mov_b32 m0, s47
	s_nop 0
	global_load_lds_dwordx4 v[4:5], off
	v_lshl_add_u64 v[4:5], v[2:3], 0, s[36:37]
	s_mov_b32 m0, s60
	s_mov_b64 s[60:61], 0x20780
	global_load_lds_dwordx4 v[4:5], off
	v_lshl_add_u64 v[4:5], v[2:3], 0, s[60:61]
	s_mov_b32 m0, s33
	s_mov_b64 s[60:61], 0x40780
	global_load_lds_dwordx4 v[4:5], off
	v_lshl_add_u64 v[4:5], v[2:3], 0, s[60:61]
	s_mov_b32 m0, s5
	s_mov_b64 s[60:61], 0x60780
	global_load_lds_dwordx4 v[4:5], off
	v_lshl_add_u64 v[2:3], v[2:3], 0, s[60:61]
	s_mov_b32 m0, s2
	s_nop 0
	global_load_lds_dwordx4 v[2:3], off
	ds_read_b128 v[2:5], v10 offset:49152
	ds_read_b128 v[72:75], v10 offset:51200
	ds_read_b128 v[76:79], v10 offset:53248
	ds_read_b128 v[92:95], v10 offset:55296
	ds_read_b128 v[96:99], v13
	ds_read_b128 v[100:103], v13 offset:2048
	ds_read_b128 v[104:107], v13 offset:4096
	ds_read_b128 v[108:111], v13 offset:6144
	s_waitcnt lgkmcnt(8)
	v_mfma_f32_16x16x32_bf16 v[80:83], v[132:135], v[116:119], v[80:83]
	v_mfma_f32_16x16x32_bf16 v[84:87], v[136:139], v[116:119], v[84:87]
	v_mfma_f32_16x16x32_bf16 v[88:91], v[140:143], v[116:119], v[88:91]
	v_mfma_f32_16x16x32_bf16 v[22:25], v[144:147], v[116:119], v[22:25]
	v_mfma_f32_16x16x32_bf16 v[38:41], v[132:135], v[120:123], v[38:41]
	v_mfma_f32_16x16x32_bf16 v[46:49], v[136:139], v[120:123], v[46:49]
	v_mfma_f32_16x16x32_bf16 v[58:61], v[140:143], v[120:123], v[58:61]
	v_mfma_f32_16x16x32_bf16 v[50:53], v[144:147], v[120:123], v[50:53]
	v_mfma_f32_16x16x32_bf16 v[42:45], v[132:135], v[124:127], v[42:45]
	v_mfma_f32_16x16x32_bf16 v[62:65], v[136:139], v[124:127], v[62:65]
	v_mfma_f32_16x16x32_bf16 v[68:71], v[140:143], v[124:127], v[68:71]
	v_mfma_f32_16x16x32_bf16 v[54:57], v[144:147], v[124:127], v[54:57]
	v_mfma_f32_16x16x32_bf16 v[34:37], v[132:135], v[128:131], v[34:37]
	v_mfma_f32_16x16x32_bf16 v[30:33], v[136:139], v[128:131], v[30:33]
	v_mfma_f32_16x16x32_bf16 v[26:29], v[140:143], v[128:131], v[26:29]
	v_mfma_f32_16x16x32_bf16 v[18:21], v[144:147], v[128:131], v[18:21]
	s_waitcnt vmcnt(6) lgkmcnt(0)
	s_barrier
	ds_read_b128 v[112:115], v14
	ds_read_b128 v[116:119], v14 offset:2048
	ds_read_b128 v[120:123], v14 offset:4096
	ds_read_b128 v[124:127], v14 offset:6144
	ds_read_b128 v[128:131], v15
	ds_read_b128 v[132:135], v15 offset:2048
	ds_read_b128 v[136:139], v15 offset:4096
	ds_read_b128 v[12:15], v15 offset:6144
	v_mfma_f32_16x16x32_bf16 v[80:83], v[96:99], v[2:5], v[80:83]
	v_mfma_f32_16x16x32_bf16 v[84:87], v[100:103], v[2:5], v[84:87]
	v_mfma_f32_16x16x32_bf16 v[88:91], v[104:107], v[2:5], v[88:91]
	v_mfma_f32_16x16x32_bf16 v[2:5], v[108:111], v[2:5], v[22:25]
	v_mfma_f32_16x16x32_bf16 v[22:25], v[96:99], v[72:75], v[38:41]
	v_mfma_f32_16x16x32_bf16 v[38:41], v[100:103], v[72:75], v[46:49]
	v_mfma_f32_16x16x32_bf16 v[46:49], v[104:107], v[72:75], v[58:61]
	v_mfma_f32_16x16x32_bf16 v[50:53], v[108:111], v[72:75], v[50:53]
	v_mfma_f32_16x16x32_bf16 v[42:45], v[96:99], v[76:79], v[42:45]
	v_mfma_f32_16x16x32_bf16 v[58:61], v[100:103], v[76:79], v[62:65]
	v_mfma_f32_16x16x32_bf16 v[62:65], v[104:107], v[76:79], v[68:71]
	v_mfma_f32_16x16x32_bf16 v[54:57], v[108:111], v[76:79], v[54:57]
	v_mfma_f32_16x16x32_bf16 v[34:37], v[96:99], v[92:95], v[34:37]
	v_mfma_f32_16x16x32_bf16 v[30:33], v[100:103], v[92:95], v[30:33]
	v_mfma_f32_16x16x32_bf16 v[26:29], v[104:107], v[92:95], v[26:29]
	v_mfma_f32_16x16x32_bf16 v[18:21], v[108:111], v[92:95], v[18:21]
	ds_read_b128 v[68:71], v16
	ds_read_b128 v[72:75], v16 offset:2048
	ds_read_b128 v[76:79], v16 offset:4096
	ds_read_b128 v[92:95], v16 offset:6144
	ds_read_b128 v[96:99], v17
	ds_read_b128 v[100:103], v17 offset:2048
	ds_read_b128 v[104:107], v17 offset:4096
	ds_read_b128 v[108:111], v17 offset:6144
	s_waitcnt lgkmcnt(8)
	v_mfma_f32_16x16x32_bf16 v[80:83], v[128:131], v[112:115], v[80:83]
	v_mfma_f32_16x16x32_bf16 v[84:87], v[132:135], v[112:115], v[84:87]
	v_mfma_f32_16x16x32_bf16 v[88:91], v[136:139], v[112:115], v[88:91]
	v_mfma_f32_16x16x32_bf16 v[2:5], v[12:15], v[112:115], v[2:5]
	v_mfma_f32_16x16x32_bf16 v[22:25], v[128:131], v[116:119], v[22:25]
	v_mfma_f32_16x16x32_bf16 v[38:41], v[132:135], v[116:119], v[38:41]
	v_mfma_f32_16x16x32_bf16 v[46:49], v[136:139], v[116:119], v[46:49]
	v_mfma_f32_16x16x32_bf16 v[50:53], v[12:15], v[116:119], v[50:53]
	v_mfma_f32_16x16x32_bf16 v[42:45], v[128:131], v[120:123], v[42:45]
	v_mfma_f32_16x16x32_bf16 v[58:61], v[132:135], v[120:123], v[58:61]
	v_mfma_f32_16x16x32_bf16 v[62:65], v[136:139], v[120:123], v[62:65]
	v_mfma_f32_16x16x32_bf16 v[54:57], v[12:15], v[120:123], v[54:57]
	v_mfma_f32_16x16x32_bf16 v[34:37], v[128:131], v[124:127], v[34:37]
	v_mfma_f32_16x16x32_bf16 v[30:33], v[132:135], v[124:127], v[30:33]
	v_mfma_f32_16x16x32_bf16 v[26:29], v[136:139], v[124:127], v[26:29]
	v_mfma_f32_16x16x32_bf16 v[12:15], v[12:15], v[124:127], v[18:21]
	s_waitcnt vmcnt(0) lgkmcnt(0)
	s_barrier
	s_nop 1
	ds_read_b128 v[16:19], v8
	ds_read_b128 v[112:115], v8 offset:2048
	ds_read_b128 v[116:119], v8 offset:4096
	ds_read_b128 v[120:123], v8 offset:6144
	ds_read_b128 v[124:127], v9 offset:16384
	ds_read_b128 v[128:131], v9 offset:18432
	ds_read_b128 v[132:135], v9 offset:20480
	ds_read_b128 v[6:9], v9 offset:22528
	v_mfma_f32_16x16x32_bf16 v[80:83], v[96:99], v[68:71], v[80:83]
	v_mfma_f32_16x16x32_bf16 v[84:87], v[100:103], v[68:71], v[84:87]
	v_mfma_f32_16x16x32_bf16 v[88:91], v[104:107], v[68:71], v[88:91]
	v_mfma_f32_16x16x32_bf16 v[2:5], v[108:111], v[68:71], v[2:5]
	v_mfma_f32_16x16x32_bf16 v[20:23], v[96:99], v[72:75], v[22:25]
	v_mfma_f32_16x16x32_bf16 v[38:41], v[100:103], v[72:75], v[38:41]
	v_mfma_f32_16x16x32_bf16 v[46:49], v[104:107], v[72:75], v[46:49]
	v_mfma_f32_16x16x32_bf16 v[50:53], v[108:111], v[72:75], v[50:53]
	v_mfma_f32_16x16x32_bf16 v[42:45], v[96:99], v[76:79], v[42:45]
	v_mfma_f32_16x16x32_bf16 v[58:61], v[100:103], v[76:79], v[58:61]
	v_mfma_f32_16x16x32_bf16 v[62:65], v[104:107], v[76:79], v[62:65]
	v_mfma_f32_16x16x32_bf16 v[54:57], v[108:111], v[76:79], v[54:57]
	v_mfma_f32_16x16x32_bf16 v[34:37], v[96:99], v[92:95], v[34:37]
	v_mfma_f32_16x16x32_bf16 v[30:33], v[100:103], v[92:95], v[30:33]
	v_mfma_f32_16x16x32_bf16 v[24:27], v[104:107], v[92:95], v[26:29]
	v_mfma_f32_16x16x32_bf16 v[12:15], v[108:111], v[92:95], v[12:15]
	ds_read_b128 v[68:71], v10
	ds_read_b128 v[72:75], v10 offset:2048
	ds_read_b128 v[76:79], v10 offset:4096
	ds_read_b128 v[92:95], v10 offset:6144
	ds_read_b128 v[96:99], v11 offset:16384
	ds_read_b128 v[100:103], v11 offset:18432
	ds_read_b128 v[104:107], v11 offset:20480
	ds_read_b128 v[108:111], v11 offset:22528
	s_waitcnt lgkmcnt(8)
	v_mfma_f32_16x16x32_bf16 v[80:83], v[124:127], v[16:19], v[80:83]
	v_mfma_f32_16x16x32_bf16 v[84:87], v[128:131], v[16:19], v[84:87]
	v_mfma_f32_16x16x32_bf16 v[88:91], v[132:135], v[16:19], v[88:91]
	v_mfma_f32_16x16x32_bf16 v[2:5], v[6:9], v[16:19], v[2:5]
	v_mfma_f32_16x16x32_bf16 v[16:19], v[124:127], v[112:115], v[20:23]
	v_mfma_f32_16x16x32_bf16 v[20:23], v[128:131], v[112:115], v[38:41]
	v_mfma_f32_16x16x32_bf16 v[38:41], v[132:135], v[112:115], v[46:49]
	v_mfma_f32_16x16x32_bf16 v[112:115], v[6:9], v[112:115], v[50:53]
	v_mfma_f32_16x16x32_bf16 v[136:139], v[124:127], v[116:119], v[42:45]
	v_mfma_f32_16x16x32_bf16 v[140:143], v[128:131], v[116:119], v[58:61]
	v_mfma_f32_16x16x32_bf16 v[144:147], v[132:135], v[116:119], v[62:65]
	v_mfma_f32_16x16x32_bf16 v[116:119], v[6:9], v[116:119], v[54:57]
	v_mfma_f32_16x16x32_bf16 v[124:127], v[124:127], v[120:123], v[34:37]
	v_mfma_f32_16x16x32_bf16 v[128:131], v[128:131], v[120:123], v[30:33]
	v_mfma_f32_16x16x32_bf16 v[132:135], v[132:135], v[120:123], v[24:27]
	v_mfma_f32_16x16x32_bf16 v[120:123], v[6:9], v[120:123], v[12:15]
	s_waitcnt vmcnt(0) lgkmcnt(0)
	s_barrier
	v_mfma_f32_16x16x32_bf16 v[58:61], v[96:99], v[68:71], v[80:83]
	v_mfma_f32_16x16x32_bf16 v[62:65], v[100:103], v[68:71], v[84:87]
	v_mfma_f32_16x16x32_bf16 v[54:57], v[104:107], v[68:71], v[88:91]
	v_mfma_f32_16x16x32_bf16 v[50:53], v[108:111], v[68:71], v[2:5]
	v_mfma_f32_16x16x32_bf16 v[42:45], v[96:99], v[72:75], v[16:19]
	v_mfma_f32_16x16x32_bf16 v[46:49], v[100:103], v[72:75], v[20:23]
	v_mfma_f32_16x16x32_bf16 v[38:41], v[104:107], v[72:75], v[38:41]
	v_mfma_f32_16x16x32_bf16 v[34:37], v[108:111], v[72:75], v[112:115]
	v_mfma_f32_16x16x32_bf16 v[26:29], v[96:99], v[76:79], v[136:139]
	v_mfma_f32_16x16x32_bf16 v[30:33], v[100:103], v[76:79], v[140:143]
	v_mfma_f32_16x16x32_bf16 v[22:25], v[104:107], v[76:79], v[144:147]
	v_mfma_f32_16x16x32_bf16 v[18:21], v[108:111], v[76:79], v[116:119]
	v_mfma_f32_16x16x32_bf16 v[10:13], v[96:99], v[92:95], v[124:127]
	v_mfma_f32_16x16x32_bf16 v[14:17], v[100:103], v[92:95], v[128:131]
	v_mfma_f32_16x16x32_bf16 v[6:9], v[104:107], v[92:95], v[132:135]
	v_mfma_f32_16x16x32_bf16 v[2:5], v[108:111], v[92:95], v[120:123]
	v_ashrrev_i32_e32 v66, 2, v1
	v_and_b32_e32 v66, 0xffffffc0, v66
	v_add_u32_e32 v66, s4, v66
	s_ashr_i32 s47, s46, 31
	v_and_or_b32 v68, v1, 15, v66
	s_lshl_b64 s[4:5], s[46:47], 20
	v_ashrrev_i32_e32 v69, 31, v68
	s_add_u32 s4, s22, s4
	s_addc_u32 s5, s23, s5
	v_lshlrev_b64 v[70:71], 11, v[68:69]
	v_lshl_add_u64 v[70:71], s[4:5], 0, v[70:71]
	s_lshl_b32 s2, s59, 8
	v_lshrrev_b32_e32 v74, 1, v1
	v_lshl_add_u64 v[70:71], v[70:71], 0, s[2:3]
	v_and_b32_e32 v66, 0xc0, v1
	v_mul_f32_e32 v1, 0xbfb8aa3b, v58
	v_lshl_add_u64 v[72:73], v[70:71], 0, v[66:67]
	v_and_b32_e32 v70, 24, v74
	v_exp_f32_e32 v74, v1
	v_mul_f32_e32 v1, 0xbfb8aa3b, v59
	v_exp_f32_e32 v75, v1
	v_mov_b32_e32 v71, v67
	v_lshl_add_u64 v[72:73], v[72:73], 0, v[70:71]
	s_waitcnt lgkmcnt(0)
	v_pk_add_f32 v[74:75], v[74:75], 1.0 op_sel_hi:[1,0]
	s_barrier
	s_mov_b32 s99, 0
	s_lshr_b32 s58, s39, 7
	s_add_i32 s58, s98, s58
	s_cmpk_ge_i32 s58, 0x800
	s_cbranch_scc1 .Lpf7_p2_skip
	s_mov_b32 s59, s58
	s_cmp_lg_u32 s39, 0x8000
	s_cbranch_scc1 .Lpf7_p2_nomap
	s_lshr_b32 s60, s58, 8
	s_bfe_u32 s61, s58, 0x30005
	s_and_b32 s62, s58, 31
	s_lshr_b32 s63, s60, 2
	s_lshl_b32 s63, s63, 3
	s_add_i32 s61, s61, s63
	s_and_b32 s60, s60, 3
	s_lshr_b32 s63, s60, 1
	s_xor_b32 s60, s60, s63
	s_and_b32 s60, s60, 1
	s_lshl_b32 s63, s63, 3
	s_lshr_b32 s64, s62, 2
	s_add_i32 s63, s63, s64
	s_and_b32 s62, s62, 3
	s_lshl_b32 s60, s60, 2
	s_add_i32 s60, s60, s62
	s_lshl_b32 s61, s61, 7
	s_lshl_b32 s60, s60, 4
	s_add_i32 s61, s61, s60
	s_add_i32 s59, s61, s63
.Lpf7_p2_nomap:
	s_ashr_i32 s60, s59, 7
	s_ashr_i32 s61, s60, 31
	s_lshl_b64 s[60:61], s[60:61], 22
	s_add_u32 s60, s82, s60
	s_addc_u32 s61, s83, s61
	s_bfe_u32 s62, s59, 0x30004
	s_lshl_b32 s62, s62, 19
	s_add_u32 s60, s60, s62
	s_addc_u32 s61, s61, 0
	s_bfe_u32 s62, s59, 0x20002
	s_lshl_b32 s62, s62, 12
	s_mov_b32 s63, 0
	v_ashrrev_i32_e32 v202, 3, v0
	v_lshrrev_b32_e32 v206, 4, v0
	v_xor_b32_e32 v206, v206, v0
	v_lshlrev_b32_e32 v206, 4, v206
	v_and_b32_e32 v206, 0x70, v206
	v_mov_b32_e32 v207, 0
	v_ashrrev_i32_e32 v203, 31, v202
	v_lshlrev_b64 v[202:203], 11, v[202:203]
	v_lshl_add_u64 v[202:203], s[60:61], 0, v[202:203]
	v_lshl_add_u64 v[202:203], v[202:203], 0, v[206:207]
	v_mov_b32_e32 v208, v200
	v_ashrrev_i32_e32 v209, 31, v200
	v_mov_b32_e32 v210, v201
	v_ashrrev_i32_e32 v211, 31, v201
	v_lshl_add_u64 v[208:209], v[208:209], 0, s[62:63]
	v_lshl_add_u64 v[210:211], v[210:211], 0, s[62:63]
	v_lshlrev_b64 v[208:209], 11, v[208:209]
	v_lshlrev_b64 v[210:211], 11, v[210:211]
	v_lshl_add_u64 v[208:209], s[8:9], 0, v[208:209]
	v_lshl_add_u64 v[210:211], s[8:9], 0, v[210:211]
	v_lshl_add_u64 v[208:209], v[208:209], 0, v[206:207]
	v_lshl_add_u64 v[210:211], v[210:211], 0, v[206:207]
	v_readfirstlane_b32 s64, v0
	s_nop 3
	s_lshl_b32 s64, s64, 4
	s_and_b32 s64, s64, 0xfffffc00
	s_mov_b64 s[60:61], 0x20000
	v_lshl_add_u64 v[212:213], v[202:203], 0, s[60:61]
	s_mov_b64 s[60:61], 0x40000
	v_lshl_add_u64 v[214:215], v[202:203], 0, s[60:61]
	s_mov_b64 s[60:61], 0x60000
	v_lshl_add_u64 v[216:217], v[202:203], 0, s[60:61]
	s_mov_b64 s[60:61], 0x80
	v_lshl_add_u64 v[218:219], v[208:209], 0, s[60:61]
	s_mov_b64 s[60:61], 0x80
	v_lshl_add_u64 v[220:221], v[210:211], 0, s[60:61]
	s_mov_b64 s[60:61], 0x80
	v_lshl_add_u64 v[222:223], v[202:203], 0, s[60:61]
	s_mov_b64 s[60:61], 0x20080
	v_lshl_add_u64 v[224:225], v[202:203], 0, s[60:61]
	s_mov_b64 s[60:61], 0x40080
	v_lshl_add_u64 v[226:227], v[202:203], 0, s[60:61]
	s_mov_b64 s[60:61], 0x60080
	v_lshl_add_u64 v[228:229], v[202:203], 0, s[60:61]
	s_mov_b32 s32, s64
	s_mov_b32 s99, 1
.Lpf7_p2_skip:
	v_div_scale_f32 v1, s[46:47], v75, v75, v59
	v_rcp_f32_e32 v69, v1
	s_add_i32 s98, s98, s66
	s_add_i32 s38, s38, s39
	v_fma_f32 v76, -v1, v69, 1.0
	v_fmac_f32_e32 v69, v76, v69
	v_div_scale_f32 v76, vcc, v59, v75, v59
	v_mul_f32_e32 v77, v76, v69
	v_fma_f32 v78, -v1, v77, v76
	v_fmac_f32_e32 v77, v78, v69
	v_fma_f32 v1, -v1, v77, v76
	v_div_fmas_f32 v1, v1, v69, v77
	v_div_fixup_f32 v59, v1, v75, v59
	v_div_scale_f32 v1, s[46:47], v74, v74, v58
	v_rcp_f32_e32 v69, v1
	s_nop 0
	v_fma_f32 v75, -v1, v69, 1.0
	v_fmac_f32_e32 v69, v75, v69
	v_div_scale_f32 v75, vcc, v58, v74, v58
	v_mul_f32_e32 v76, v75, v69
	v_fma_f32 v77, -v1, v76, v75
	v_fmac_f32_e32 v76, v77, v69
	s_cmp_eq_u32 s99, 1
	s_cbranch_scc0 .Lpf7_sp0
	s_mov_b32 m0, s32
	s_nop 0
	global_load_lds_dwordx4 v[208:209], off
.Lpf7_sp0:
	v_fma_f32 v1, -v1, v76, v75
	v_div_fmas_f32 v1, v1, v69, v76
	v_div_fixup_f32 v58, v1, v74, v58
	v_mul_f32_e32 v1, 0xbfb8aa3b, v60
	v_pk_mul_f32 v[58:59], v[62:63], v[58:59]
	v_exp_f32_e32 v62, v1
	v_mul_f32_e32 v1, 0xbfb8aa3b, v61
	v_exp_f32_e32 v63, v1
	v_cvt_pk_bf16_f32 v58, v58, v59
	v_pk_add_f32 v[62:63], v[62:63], 1.0 op_sel_hi:[1,0]
	s_nop 0
	v_div_scale_f32 v1, s[46:47], v63, v63, v61
	v_rcp_f32_e32 v69, v1
	s_nop 0
	v_fma_f32 v74, -v1, v69, 1.0
	v_fmac_f32_e32 v69, v74, v69
	v_div_scale_f32 v74, vcc, v61, v63, v61
	v_mul_f32_e32 v75, v74, v69
	v_fma_f32 v76, -v1, v75, v74
	v_fmac_f32_e32 v75, v76, v69
	v_fma_f32 v1, -v1, v75, v74
	v_div_fmas_f32 v1, v1, v69, v75
	v_div_fixup_f32 v61, v1, v63, v61
	v_div_scale_f32 v1, s[46:47], v62, v62, v60
	v_rcp_f32_e32 v63, v1
	s_nop 0
	v_fma_f32 v69, -v1, v63, 1.0
	v_fmac_f32_e32 v63, v69, v63
	v_div_scale_f32 v69, vcc, v60, v62, v60
	v_mul_f32_e32 v74, v69, v63
	v_fma_f32 v75, -v1, v74, v69
	v_fmac_f32_e32 v74, v75, v63
	v_fma_f32 v1, -v1, v74, v69
	v_div_fmas_f32 v1, v1, v63, v74
	v_div_fixup_f32 v60, v1, v62, v60
	v_pk_mul_f32 v[60:61], v[64:65], v[60:61]
	v_mul_f32_e32 v1, 0xbfb8aa3b, v54
	v_cvt_pk_bf16_f32 v59, v60, v61
	global_store_dwordx2 v[72:73], v[58:59], off
	v_exp_f32_e32 v58, v1
	v_mul_f32_e32 v1, 0xbfb8aa3b, v55
	v_exp_f32_e32 v59, v1
	s_nop 0
	v_pk_add_f32 v[58:59], v[58:59], 1.0 op_sel_hi:[1,0]
	s_cmp_eq_u32 s99, 1
	s_cbranch_scc0 .Lpf7_sp1
	s_add_i32 m0, s32, 0x2000
	s_nop 0
	global_load_lds_dwordx4 v[210:211], off
.Lpf7_sp1:
	s_nop 0
	v_div_scale_f32 v1, s[46:47], v59, v59, v55
	v_rcp_f32_e32 v60, v1
	s_nop 0
	v_fma_f32 v61, -v1, v60, 1.0
	v_fmac_f32_e32 v60, v61, v60
	v_div_scale_f32 v61, vcc, v55, v59, v55
	v_mul_f32_e32 v62, v61, v60
	v_fma_f32 v63, -v1, v62, v61
	v_fmac_f32_e32 v62, v63, v60
	v_fma_f32 v1, -v1, v62, v61
	v_div_fmas_f32 v1, v1, v60, v62
	v_div_fixup_f32 v55, v1, v59, v55
	v_div_scale_f32 v1, s[46:47], v58, v58, v54
	v_rcp_f32_e32 v59, v1
	s_nop 0
	v_fma_f32 v60, -v1, v59, 1.0
	v_fmac_f32_e32 v59, v60, v59
	v_div_scale_f32 v60, vcc, v54, v58, v54
	v_mul_f32_e32 v61, v60, v59
	v_fma_f32 v62, -v1, v61, v60
	v_fmac_f32_e32 v61, v62, v59
	v_fma_f32 v1, -v1, v61, v60
	v_div_fmas_f32 v1, v1, v59, v61
	v_div_fixup_f32 v54, v1, v58, v54
	v_mul_f32_e32 v1, 0xbfb8aa3b, v56
	v_pk_mul_f32 v[50:51], v[50:51], v[54:55]
	v_exp_f32_e32 v54, v1
	v_mul_f32_e32 v1, 0xbfb8aa3b, v57
	v_exp_f32_e32 v55, v1
	v_cvt_pk_bf16_f32 v50, v50, v51
	v_pk_add_f32 v[54:55], v[54:55], 1.0 op_sel_hi:[1,0]
	s_nop 0
	v_div_scale_f32 v1, s[46:47], v55, v55, v57
	v_rcp_f32_e32 v58, v1
	s_nop 0
	v_fma_f32 v59, -v1, v58, 1.0
	v_fmac_f32_e32 v58, v59, v58
	v_div_scale_f32 v59, vcc, v57, v55, v57
	v_mul_f32_e32 v60, v59, v58
	v_fma_f32 v61, -v1, v60, v59
	v_fmac_f32_e32 v60, v61, v58
	v_fma_f32 v1, -v1, v60, v59
	v_div_fmas_f32 v1, v1, v58, v60
	v_div_fixup_f32 v55, v1, v55, v57
	s_cmp_eq_u32 s99, 1
	s_cbranch_scc0 .Lpf7_sp2
	s_add_i32 m0, s32, 0x4000
	s_nop 0
	global_load_lds_dwordx4 v[202:203], off
.Lpf7_sp2:
	v_div_scale_f32 v1, s[46:47], v54, v54, v56
	v_rcp_f32_e32 v57, v1
	s_nop 0
	v_fma_f32 v58, -v1, v57, 1.0
	v_fmac_f32_e32 v57, v58, v57
	v_div_scale_f32 v58, vcc, v56, v54, v56
	v_mul_f32_e32 v59, v58, v57
	v_fma_f32 v60, -v1, v59, v58
	v_fmac_f32_e32 v59, v60, v57
	v_fma_f32 v1, -v1, v59, v58
	v_div_fmas_f32 v1, v1, v57, v59
	v_div_fixup_f32 v54, v1, v54, v56
	v_pk_mul_f32 v[52:53], v[52:53], v[54:55]
	v_mul_f32_e32 v1, 0xbfb8aa3b, v42
	v_cvt_pk_bf16_f32 v51, v52, v53
	v_exp_f32_e32 v52, v1
	v_mul_f32_e32 v1, 0xbfb8aa3b, v43
	v_exp_f32_e32 v53, v1
	global_store_dwordx2 v[72:73], v[50:51], off offset:32
	v_or_b32_e32 v50, 16, v68
	v_ashrrev_i32_e32 v51, 31, v50
	v_pk_add_f32 v[52:53], v[52:53], 1.0 op_sel_hi:[1,0]
	v_lshlrev_b64 v[50:51], 11, v[50:51]
	v_div_scale_f32 v1, s[46:47], v53, v53, v43
	v_rcp_f32_e32 v54, v1
	v_lshl_add_u64 v[50:51], s[4:5], 0, v[50:51]
	v_lshl_add_u64 v[50:51], v[50:51], 0, s[2:3]
	v_lshl_add_u64 v[50:51], v[50:51], 0, v[66:67]
	v_fma_f32 v55, -v1, v54, 1.0
	v_fmac_f32_e32 v54, v55, v54
	v_div_scale_f32 v55, vcc, v43, v53, v43
	v_mul_f32_e32 v56, v55, v54
	v_fma_f32 v57, -v1, v56, v55
	v_fmac_f32_e32 v56, v57, v54
	v_fma_f32 v1, -v1, v56, v55
	v_div_fmas_f32 v1, v1, v54, v56
	v_div_fixup_f32 v43, v1, v53, v43
	v_div_scale_f32 v1, s[46:47], v52, v52, v42
	v_rcp_f32_e32 v53, v1
	v_lshl_add_u64 v[50:51], v[50:51], 0, v[70:71]
	v_fma_f32 v54, -v1, v53, 1.0
	v_fmac_f32_e32 v53, v54, v53
	v_div_scale_f32 v54, vcc, v42, v52, v42
	v_mul_f32_e32 v55, v54, v53
	s_cmp_eq_u32 s99, 1
	s_cbranch_scc0 .Lpf7_sp3
	s_add_i32 m0, s32, 0x6000
	s_nop 0
	global_load_lds_dwordx4 v[212:213], off
.Lpf7_sp3:
	v_fma_f32 v56, -v1, v55, v54
	v_fmac_f32_e32 v55, v56, v53
	v_fma_f32 v1, -v1, v55, v54
	v_div_fmas_f32 v1, v1, v53, v55
	v_div_fixup_f32 v42, v1, v52, v42
	v_mul_f32_e32 v1, 0xbfb8aa3b, v44
	v_pk_mul_f32 v[42:43], v[46:47], v[42:43]
	v_exp_f32_e32 v46, v1
	v_mul_f32_e32 v1, 0xbfb8aa3b, v45
	v_exp_f32_e32 v47, v1
	v_cvt_pk_bf16_f32 v42, v42, v43
	v_pk_add_f32 v[46:47], v[46:47], 1.0 op_sel_hi:[1,0]
	s_nop 0
	v_div_scale_f32 v1, s[46:47], v47, v47, v45
	v_rcp_f32_e32 v52, v1
	s_nop 0
	v_fma_f32 v53, -v1, v52, 1.0
	v_fmac_f32_e32 v52, v53, v52
	v_div_scale_f32 v53, vcc, v45, v47, v45
	v_mul_f32_e32 v54, v53, v52
	v_fma_f32 v55, -v1, v54, v53
	v_fmac_f32_e32 v54, v55, v52
	v_fma_f32 v1, -v1, v54, v53
	v_div_fmas_f32 v1, v1, v52, v54
	v_div_fixup_f32 v45, v1, v47, v45
	v_div_scale_f32 v1, s[46:47], v46, v46, v44
	v_rcp_f32_e32 v47, v1
	s_nop 0
	v_fma_f32 v52, -v1, v47, 1.0
	v_fmac_f32_e32 v47, v52, v47
	v_div_scale_f32 v52, vcc, v44, v46, v44
	v_mul_f32_e32 v53, v52, v47
	v_fma_f32 v54, -v1, v53, v52
	v_fmac_f32_e32 v53, v54, v47
	v_fma_f32 v1, -v1, v53, v52
	v_div_fmas_f32 v1, v1, v47, v53
	v_div_fixup_f32 v44, v1, v46, v44
	v_pk_mul_f32 v[44:45], v[48:49], v[44:45]
	v_mul_f32_e32 v1, 0xbfb8aa3b, v38
	v_cvt_pk_bf16_f32 v43, v44, v45
	global_store_dwordx2 v[50:51], v[42:43], off
	v_exp_f32_e32 v42, v1
	v_mul_f32_e32 v1, 0xbfb8aa3b, v39
	v_exp_f32_e32 v43, v1
	s_cmp_eq_u32 s99, 1
	s_cbranch_scc0 .Lpf7_sp4
	s_add_i32 m0, s32, 0x8000
	s_nop 0
	global_load_lds_dwordx4 v[214:215], off
.Lpf7_sp4:
	s_nop 0
	v_pk_add_f32 v[42:43], v[42:43], 1.0 op_sel_hi:[1,0]
	s_nop 0
	v_div_scale_f32 v1, s[46:47], v43, v43, v39
	v_rcp_f32_e32 v44, v1
	s_nop 0
	v_fma_f32 v45, -v1, v44, 1.0
	v_fmac_f32_e32 v44, v45, v44
	v_div_scale_f32 v45, vcc, v39, v43, v39
	v_mul_f32_e32 v46, v45, v44
	v_fma_f32 v47, -v1, v46, v45
	v_fmac_f32_e32 v46, v47, v44
	v_fma_f32 v1, -v1, v46, v45
	v_div_fmas_f32 v1, v1, v44, v46
	v_div_fixup_f32 v39, v1, v43, v39
	v_div_scale_f32 v1, s[46:47], v42, v42, v38
	v_rcp_f32_e32 v43, v1
	s_nop 0
	v_fma_f32 v44, -v1, v43, 1.0
	v_fmac_f32_e32 v43, v44, v43
	v_div_scale_f32 v44, vcc, v38, v42, v38
	v_mul_f32_e32 v45, v44, v43
	v_fma_f32 v46, -v1, v45, v44
	v_fmac_f32_e32 v45, v46, v43
	v_fma_f32 v1, -v1, v45, v44
	v_div_fmas_f32 v1, v1, v43, v45
	v_div_fixup_f32 v38, v1, v42, v38
	v_mul_f32_e32 v1, 0xbfb8aa3b, v40
	v_pk_mul_f32 v[34:35], v[34:35], v[38:39]
	v_exp_f32_e32 v38, v1
	v_mul_f32_e32 v1, 0xbfb8aa3b, v41
	v_exp_f32_e32 v39, v1
	v_cvt_pk_bf16_f32 v34, v34, v35
	v_pk_add_f32 v[38:39], v[38:39], 1.0 op_sel_hi:[1,0]
	s_nop 0
	v_div_scale_f32 v1, s[46:47], v39, v39, v41
	v_rcp_f32_e32 v42, v1
	s_nop 0
	v_fma_f32 v43, -v1, v42, 1.0
	v_fmac_f32_e32 v42, v43, v42
	v_div_scale_f32 v43, vcc, v41, v39, v41
	v_mul_f32_e32 v44, v43, v42
	v_fma_f32 v45, -v1, v44, v43
	v_fmac_f32_e32 v44, v45, v42
	v_fma_f32 v1, -v1, v44, v43
	s_cmp_eq_u32 s99, 1
	s_cbranch_scc0 .Lpf7_sp5
	s_add_i32 m0, s32, 0xa000
	s_nop 0
	global_load_lds_dwordx4 v[216:217], off
.Lpf7_sp5:
	v_div_fmas_f32 v1, v1, v42, v44
	v_div_fixup_f32 v39, v1, v39, v41
	v_div_scale_f32 v1, s[46:47], v38, v38, v40
	v_rcp_f32_e32 v41, v1
	s_nop 0
	v_fma_f32 v42, -v1, v41, 1.0
	v_fmac_f32_e32 v41, v42, v41
	v_div_scale_f32 v42, vcc, v40, v38, v40
	v_mul_f32_e32 v43, v42, v41
	v_fma_f32 v44, -v1, v43, v42
	v_fmac_f32_e32 v43, v44, v41
	v_fma_f32 v1, -v1, v43, v42
	v_div_fmas_f32 v1, v1, v41, v43
	v_div_fixup_f32 v38, v1, v38, v40
	v_pk_mul_f32 v[36:37], v[36:37], v[38:39]
	v_mul_f32_e32 v1, 0xbfb8aa3b, v26
	v_cvt_pk_bf16_f32 v35, v36, v37
	v_exp_f32_e32 v36, v1
	v_mul_f32_e32 v1, 0xbfb8aa3b, v27
	v_exp_f32_e32 v37, v1
	global_store_dwordx2 v[50:51], v[34:35], off offset:32
	v_or_b32_e32 v34, 32, v68
	v_ashrrev_i32_e32 v35, 31, v34
	v_pk_add_f32 v[36:37], v[36:37], 1.0 op_sel_hi:[1,0]
	v_lshlrev_b64 v[34:35], 11, v[34:35]
	v_div_scale_f32 v1, s[46:47], v37, v37, v27
	v_rcp_f32_e32 v38, v1
	v_lshl_add_u64 v[34:35], s[4:5], 0, v[34:35]
	v_lshl_add_u64 v[34:35], v[34:35], 0, s[2:3]
	v_lshl_add_u64 v[34:35], v[34:35], 0, v[66:67]
	v_fma_f32 v39, -v1, v38, 1.0
	v_fmac_f32_e32 v38, v39, v38
	v_div_scale_f32 v39, vcc, v27, v37, v27
	v_mul_f32_e32 v40, v39, v38
	v_fma_f32 v41, -v1, v40, v39
	v_fmac_f32_e32 v40, v41, v38
	v_fma_f32 v1, -v1, v40, v39
	v_div_fmas_f32 v1, v1, v38, v40
	v_div_fixup_f32 v27, v1, v37, v27
	v_div_scale_f32 v1, s[46:47], v36, v36, v26
	v_rcp_f32_e32 v37, v1
	v_lshl_add_u64 v[34:35], v[34:35], 0, v[70:71]
	v_fma_f32 v38, -v1, v37, 1.0
	v_fmac_f32_e32 v37, v38, v37
	s_cmp_eq_u32 s99, 1
	s_cbranch_scc0 .Lpf7_sp6
	s_add_i32 m0, s32, 0xc000
	s_nop 0
	global_load_lds_dwordx4 v[218:219], off
.Lpf7_sp6:
	v_div_scale_f32 v38, vcc, v26, v36, v26
	v_mul_f32_e32 v39, v38, v37
	v_fma_f32 v40, -v1, v39, v38
	v_fmac_f32_e32 v39, v40, v37
	v_fma_f32 v1, -v1, v39, v38
	v_div_fmas_f32 v1, v1, v37, v39
	v_div_fixup_f32 v26, v1, v36, v26
	v_mul_f32_e32 v1, 0xbfb8aa3b, v28
	v_pk_mul_f32 v[26:27], v[30:31], v[26:27]
	v_exp_f32_e32 v30, v1
	v_mul_f32_e32 v1, 0xbfb8aa3b, v29
	v_exp_f32_e32 v31, v1
	v_cvt_pk_bf16_f32 v26, v26, v27
	v_pk_add_f32 v[30:31], v[30:31], 1.0 op_sel_hi:[1,0]
	s_nop 0
	v_div_scale_f32 v1, s[46:47], v31, v31, v29
	v_rcp_f32_e32 v36, v1
	s_nop 0
	v_fma_f32 v37, -v1, v36, 1.0
	v_fmac_f32_e32 v36, v37, v36
	v_div_scale_f32 v37, vcc, v29, v31, v29
	v_mul_f32_e32 v38, v37, v36
	v_fma_f32 v39, -v1, v38, v37
	v_fmac_f32_e32 v38, v39, v36
	v_fma_f32 v1, -v1, v38, v37
	v_div_fmas_f32 v1, v1, v36, v38
	v_div_fixup_f32 v29, v1, v31, v29
	v_div_scale_f32 v1, s[46:47], v30, v30, v28
	v_rcp_f32_e32 v31, v1
	s_nop 0
	v_fma_f32 v36, -v1, v31, 1.0
	v_fmac_f32_e32 v31, v36, v31
	v_div_scale_f32 v36, vcc, v28, v30, v28
	v_mul_f32_e32 v37, v36, v31
	v_fma_f32 v38, -v1, v37, v36
	v_fmac_f32_e32 v37, v38, v31
	v_fma_f32 v1, -v1, v37, v36
	v_div_fmas_f32 v1, v1, v31, v37
	v_div_fixup_f32 v28, v1, v30, v28
	v_pk_mul_f32 v[28:29], v[32:33], v[28:29]
	v_mul_f32_e32 v1, 0xbfb8aa3b, v22
	v_cvt_pk_bf16_f32 v27, v28, v29
	global_store_dwordx2 v[34:35], v[26:27], off
	v_exp_f32_e32 v26, v1
	v_mul_f32_e32 v1, 0xbfb8aa3b, v23
	s_cmp_eq_u32 s99, 1
	s_cbranch_scc0 .Lpf7_sp7
	s_add_i32 m0, s32, 0xe000
	s_nop 0
	global_load_lds_dwordx4 v[220:221], off
.Lpf7_sp7:
	v_exp_f32_e32 v27, v1
	s_nop 0
	v_pk_add_f32 v[26:27], v[26:27], 1.0 op_sel_hi:[1,0]
	s_nop 0
	v_div_scale_f32 v1, s[46:47], v27, v27, v23
	v_rcp_f32_e32 v28, v1
	s_nop 0
	v_fma_f32 v29, -v1, v28, 1.0
	v_fmac_f32_e32 v28, v29, v28
	v_div_scale_f32 v29, vcc, v23, v27, v23
	v_mul_f32_e32 v30, v29, v28
	v_fma_f32 v31, -v1, v30, v29
	v_fmac_f32_e32 v30, v31, v28
	v_fma_f32 v1, -v1, v30, v29
	v_div_fmas_f32 v1, v1, v28, v30
	v_div_fixup_f32 v23, v1, v27, v23
	v_div_scale_f32 v1, s[46:47], v26, v26, v22
	v_rcp_f32_e32 v27, v1
	s_nop 0
	v_fma_f32 v28, -v1, v27, 1.0
	v_fmac_f32_e32 v27, v28, v27
	v_div_scale_f32 v28, vcc, v22, v26, v22
	v_mul_f32_e32 v29, v28, v27
	v_fma_f32 v30, -v1, v29, v28
	v_fmac_f32_e32 v29, v30, v27
	v_fma_f32 v1, -v1, v29, v28
	v_div_fmas_f32 v1, v1, v27, v29
	v_div_fixup_f32 v22, v1, v26, v22
	v_mul_f32_e32 v1, 0xbfb8aa3b, v24
	v_pk_mul_f32 v[18:19], v[18:19], v[22:23]
	v_exp_f32_e32 v22, v1
	v_mul_f32_e32 v1, 0xbfb8aa3b, v25
	v_exp_f32_e32 v23, v1
	v_cvt_pk_bf16_f32 v18, v18, v19
	v_pk_add_f32 v[22:23], v[22:23], 1.0 op_sel_hi:[1,0]
	s_nop 0
	v_div_scale_f32 v1, s[46:47], v23, v23, v25
	v_rcp_f32_e32 v26, v1
	s_nop 0
	v_fma_f32 v27, -v1, v26, 1.0
	v_fmac_f32_e32 v26, v27, v26
	v_div_scale_f32 v27, vcc, v25, v23, v25
	v_mul_f32_e32 v28, v27, v26
	v_fma_f32 v29, -v1, v28, v27
	s_cmp_eq_u32 s99, 1
	s_cbranch_scc0 .Lpf7_sp8
	s_add_i32 m0, s32, 0x10000
	s_nop 0
	global_load_lds_dwordx4 v[222:223], off
.Lpf7_sp8:
	v_fmac_f32_e32 v28, v29, v26
	v_fma_f32 v1, -v1, v28, v27
	v_div_fmas_f32 v1, v1, v26, v28
	v_div_fixup_f32 v23, v1, v23, v25
	v_div_scale_f32 v1, s[46:47], v22, v22, v24
	v_rcp_f32_e32 v25, v1
	s_nop 0
	v_fma_f32 v26, -v1, v25, 1.0
	v_fmac_f32_e32 v25, v26, v25
	v_div_scale_f32 v26, vcc, v24, v22, v24
	v_mul_f32_e32 v27, v26, v25
	v_fma_f32 v28, -v1, v27, v26
	v_fmac_f32_e32 v27, v28, v25
	v_fma_f32 v1, -v1, v27, v26
	v_div_fmas_f32 v1, v1, v25, v27
	v_div_fixup_f32 v22, v1, v22, v24
	v_pk_mul_f32 v[20:21], v[20:21], v[22:23]
	v_mul_f32_e32 v1, 0xbfb8aa3b, v10
	v_cvt_pk_bf16_f32 v19, v20, v21
	v_exp_f32_e32 v20, v1
	v_mul_f32_e32 v1, 0xbfb8aa3b, v11
	v_exp_f32_e32 v21, v1
	global_store_dwordx2 v[34:35], v[18:19], off offset:32
	v_or_b32_e32 v18, 48, v68
	v_ashrrev_i32_e32 v19, 31, v18
	v_lshlrev_b64 v[18:19], 11, v[18:19]
	v_pk_add_f32 v[20:21], v[20:21], 1.0 op_sel_hi:[1,0]
	v_lshl_add_u64 v[18:19], s[4:5], 0, v[18:19]
	v_div_scale_f32 v1, s[4:5], v21, v21, v11
	v_rcp_f32_e32 v22, v1
	v_lshl_add_u64 v[18:19], v[18:19], 0, s[2:3]
	v_lshl_add_u64 v[18:19], v[18:19], 0, v[66:67]
	v_lshl_add_u64 v[18:19], v[18:19], 0, v[70:71]
	v_fma_f32 v23, -v1, v22, 1.0
	v_fmac_f32_e32 v22, v23, v22
	v_div_scale_f32 v23, vcc, v11, v21, v11
	v_mul_f32_e32 v24, v23, v22
	v_fma_f32 v25, -v1, v24, v23
	v_fmac_f32_e32 v24, v25, v22
	v_fma_f32 v1, -v1, v24, v23
	v_div_fmas_f32 v1, v1, v22, v24
	v_div_fixup_f32 v11, v1, v21, v11
	v_div_scale_f32 v1, s[4:5], v20, v20, v10
	v_rcp_f32_e32 v21, v1
	s_cmp_eq_u32 s99, 1
	s_cbranch_scc0 .Lpf7_sp9
	s_add_i32 m0, s32, 0x12000
	s_nop 0
	global_load_lds_dwordx4 v[224:225], off
.Lpf7_sp9:
	s_nop 0
	v_fma_f32 v22, -v1, v21, 1.0
	v_fmac_f32_e32 v21, v22, v21
	v_div_scale_f32 v22, vcc, v10, v20, v10
	v_mul_f32_e32 v23, v22, v21
	v_fma_f32 v24, -v1, v23, v22
	v_fmac_f32_e32 v23, v24, v21
	v_fma_f32 v1, -v1, v23, v22
	v_div_fmas_f32 v1, v1, v21, v23
	v_div_fixup_f32 v10, v1, v20, v10
	v_mul_f32_e32 v1, 0xbfb8aa3b, v12
	v_pk_mul_f32 v[10:11], v[14:15], v[10:11]
	v_exp_f32_e32 v14, v1
	v_mul_f32_e32 v1, 0xbfb8aa3b, v13
	v_exp_f32_e32 v15, v1
	v_cvt_pk_bf16_f32 v10, v10, v11
	v_pk_add_f32 v[14:15], v[14:15], 1.0 op_sel_hi:[1,0]
	s_nop 0
	v_div_scale_f32 v1, s[4:5], v15, v15, v13
	v_rcp_f32_e32 v20, v1
	s_nop 0
	v_fma_f32 v21, -v1, v20, 1.0
	v_fmac_f32_e32 v20, v21, v20
	v_div_scale_f32 v21, vcc, v13, v15, v13
	v_mul_f32_e32 v22, v21, v20
	v_fma_f32 v23, -v1, v22, v21
	v_fmac_f32_e32 v22, v23, v20
	v_fma_f32 v1, -v1, v22, v21
	v_div_fmas_f32 v1, v1, v20, v22
	v_div_fixup_f32 v13, v1, v15, v13
	v_div_scale_f32 v1, s[4:5], v14, v14, v12
	v_rcp_f32_e32 v15, v1
	s_nop 0
	v_fma_f32 v20, -v1, v15, 1.0
	v_fmac_f32_e32 v15, v20, v15
	v_div_scale_f32 v20, vcc, v12, v14, v12
	v_mul_f32_e32 v21, v20, v15
	v_fma_f32 v22, -v1, v21, v20
	v_fmac_f32_e32 v21, v22, v15
	v_fma_f32 v1, -v1, v21, v20
	v_div_fmas_f32 v1, v1, v15, v21
	v_div_fixup_f32 v12, v1, v14, v12
	v_pk_mul_f32 v[12:13], v[16:17], v[12:13]
	v_mul_f32_e32 v1, 0xbfb8aa3b, v6
	v_cvt_pk_bf16_f32 v11, v12, v13
	s_cmp_eq_u32 s99, 1
	s_cbranch_scc0 .Lpf7_sp10
	s_add_i32 m0, s32, 0x14000
	s_nop 0
	global_load_lds_dwordx4 v[226:227], off
.Lpf7_sp10:
	global_store_dwordx2 v[18:19], v[10:11], off
	v_exp_f32_e32 v10, v1
	v_mul_f32_e32 v1, 0xbfb8aa3b, v7
	v_exp_f32_e32 v11, v1
	s_nop 0
	v_pk_add_f32 v[10:11], v[10:11], 1.0 op_sel_hi:[1,0]
	s_nop 0
	v_div_scale_f32 v1, s[4:5], v11, v11, v7
	v_rcp_f32_e32 v12, v1
	s_nop 0
	v_fma_f32 v13, -v1, v12, 1.0
	v_fmac_f32_e32 v12, v13, v12
	v_div_scale_f32 v13, vcc, v7, v11, v7
	v_mul_f32_e32 v14, v13, v12
	v_fma_f32 v15, -v1, v14, v13
	v_fmac_f32_e32 v14, v15, v12
	v_fma_f32 v1, -v1, v14, v13
	v_div_fmas_f32 v1, v1, v12, v14
	v_div_fixup_f32 v7, v1, v11, v7
	v_div_scale_f32 v1, s[4:5], v10, v10, v6
	v_rcp_f32_e32 v11, v1
	s_nop 0
	v_fma_f32 v12, -v1, v11, 1.0
	v_fmac_f32_e32 v11, v12, v11
	v_div_scale_f32 v12, vcc, v6, v10, v6
	v_mul_f32_e32 v13, v12, v11
	v_fma_f32 v14, -v1, v13, v12
	v_fmac_f32_e32 v13, v14, v11
	v_fma_f32 v1, -v1, v13, v12
	v_div_fmas_f32 v1, v1, v11, v13
	v_div_fixup_f32 v6, v1, v10, v6
	v_mul_f32_e32 v1, 0xbfb8aa3b, v8
	v_pk_mul_f32 v[2:3], v[2:3], v[6:7]
	v_exp_f32_e32 v6, v1
	v_mul_f32_e32 v1, 0xbfb8aa3b, v9
	v_exp_f32_e32 v7, v1
	v_cvt_pk_bf16_f32 v2, v2, v3
	v_pk_add_f32 v[6:7], v[6:7], 1.0 op_sel_hi:[1,0]
	s_nop 0
	v_div_scale_f32 v1, s[4:5], v7, v7, v9
	v_rcp_f32_e32 v10, v1
	s_nop 0
	v_fma_f32 v11, -v1, v10, 1.0
	v_fmac_f32_e32 v10, v11, v10
	s_cmp_eq_u32 s99, 1
	s_cbranch_scc0 .Lpf7_sp11
	s_add_i32 m0, s32, 0x16000
	s_nop 0
	global_load_lds_dwordx4 v[228:229], off
.Lpf7_sp11:
	v_div_scale_f32 v11, vcc, v9, v7, v9
	v_mul_f32_e32 v12, v11, v10
	v_fma_f32 v13, -v1, v12, v11
	v_fmac_f32_e32 v12, v13, v10
	v_fma_f32 v1, -v1, v12, v11
	v_div_fmas_f32 v1, v1, v10, v12
	v_div_fixup_f32 v7, v1, v7, v9
	v_div_scale_f32 v1, s[4:5], v6, v6, v8
	v_rcp_f32_e32 v9, v1
	s_nop 0
	v_fma_f32 v10, -v1, v9, 1.0
	v_fmac_f32_e32 v9, v10, v9
	v_div_scale_f32 v10, vcc, v8, v6, v8
	v_mul_f32_e32 v11, v10, v9
	v_fma_f32 v12, -v1, v11, v10
	v_fmac_f32_e32 v11, v12, v9
	v_fma_f32 v1, -v1, v11, v10
	v_div_fmas_f32 v1, v1, v9, v11
	v_div_fixup_f32 v6, v1, v6, v8
	v_pk_mul_f32 v[4:5], v[4:5], v[6:7]
	s_nop 0
	v_cvt_pk_bf16_f32 v3, v4, v5
	global_store_dwordx2 v[18:19], v[2:3], off offset:32
	s_cmpk_lt_i32 s98, 0x800
	s_cbranch_scc1 .LBB0_838
	v_readlane_b32 s0, v196, 26
	v_readlane_b32 s47, v196, 5
	v_readlane_b32 s96, v196, 24
	v_readlane_b32 s1, v196, 27
	s_mov_b32 s46, s66
	v_readlane_b32 s97, v196, 25

.Lpf15_p1_skip:
	ds_read_b128 v[116:119], v14
	ds_read_b128 v[120:123], v14 offset:2048
	ds_read_b128 v[124:127], v14 offset:4096
	ds_read_b128 v[128:131], v14 offset:6144
	ds_read_b128 v[132:135], v15
	ds_read_b128 v[136:139], v15 offset:2048
	ds_read_b128 v[140:143], v15 offset:4096
	ds_read_b128 v[144:147], v15 offset:6144
	v_mfma_f32_16x16x32_bf16 v[80:83], v[100:103], v[72:75], v[80:83]
	v_mfma_f32_16x16x32_bf16 v[84:87], v[104:107], v[72:75], v[84:87]
	v_mfma_f32_16x16x32_bf16 v[88:91], v[108:111], v[72:75], v[88:91]
	v_mfma_f32_16x16x32_bf16 v[22:25], v[112:115], v[72:75], v[22:25]
	v_mfma_f32_16x16x32_bf16 v[38:41], v[100:103], v[76:79], v[38:41]
	v_mfma_f32_16x16x32_bf16 v[46:49], v[104:107], v[76:79], v[46:49]
	v_mfma_f32_16x16x32_bf16 v[58:61], v[108:111], v[76:79], v[58:61]
	v_mfma_f32_16x16x32_bf16 v[50:53], v[112:115], v[76:79], v[50:53]
	v_mfma_f32_16x16x32_bf16 v[42:45], v[100:103], v[92:95], v[42:45]
	v_mfma_f32_16x16x32_bf16 v[62:65], v[104:107], v[92:95], v[62:65]
	v_mfma_f32_16x16x32_bf16 v[68:71], v[108:111], v[92:95], v[68:71]
	v_mfma_f32_16x16x32_bf16 v[54:57], v[112:115], v[92:95], v[54:57]
	v_mfma_f32_16x16x32_bf16 v[34:37], v[100:103], v[96:99], v[34:37]
	v_mfma_f32_16x16x32_bf16 v[30:33], v[104:107], v[96:99], v[30:33]
	v_mfma_f32_16x16x32_bf16 v[26:29], v[108:111], v[96:99], v[26:29]
	v_mfma_f32_16x16x32_bf16 v[18:21], v[112:115], v[96:99], v[18:21]
	s_mov_b32 m0, s66
	v_lshl_add_u64 v[72:73], v[4:5], 0, s[30:31]
	global_load_lds_dwordx4 v[72:73], off
	v_lshl_add_u64 v[72:73], v[6:7], 0, s[30:31]
	s_mov_b32 m0, s65
	s_mov_b64 s[76:77], 0x4000680
	global_load_lds_dwordx4 v[72:73], off
	v_lshl_add_u64 v[72:73], v[2:3], 0, s[76:77]
	s_mov_b32 m0, s4
	s_mov_b64 s[76:77], 0x4020680
	global_load_lds_dwordx4 v[72:73], off
	v_lshl_add_u64 v[72:73], v[2:3], 0, s[76:77]
	s_mov_b32 m0, s5
	s_mov_b64 s[4:5], 0x4040680
	global_load_lds_dwordx4 v[72:73], off
	v_lshl_add_u64 v[72:73], v[2:3], 0, s[4:5]
	v_readlane_b32 s4, v196, 22
	v_readlane_b32 s5, v196, 23
	s_mov_b32 m0, s67
	s_mov_b32 s10, s4
	s_mov_b64 s[4:5], 0x4060680
	global_load_lds_dwordx4 v[72:73], off
	v_lshl_add_u64 v[72:73], v[2:3], 0, s[4:5]
	s_mov_b32 m0, s68
	s_nop 0
	global_load_lds_dwordx4 v[72:73], off
	ds_read_b128 v[72:75], v16
	ds_read_b128 v[76:79], v16 offset:2048
	ds_read_b128 v[92:95], v16 offset:4096
	ds_read_b128 v[96:99], v16 offset:6144
	ds_read_b128 v[100:103], v17
	ds_read_b128 v[104:107], v17 offset:2048
	ds_read_b128 v[108:111], v17 offset:4096
	ds_read_b128 v[112:115], v17 offset:6144
	s_waitcnt lgkmcnt(8)
	v_mfma_f32_16x16x32_bf16 v[80:83], v[132:135], v[116:119], v[80:83]
	v_mfma_f32_16x16x32_bf16 v[84:87], v[136:139], v[116:119], v[84:87]
	v_mfma_f32_16x16x32_bf16 v[88:91], v[140:143], v[116:119], v[88:91]
	v_mfma_f32_16x16x32_bf16 v[22:25], v[144:147], v[116:119], v[22:25]
	v_mfma_f32_16x16x32_bf16 v[38:41], v[132:135], v[120:123], v[38:41]
	v_mfma_f32_16x16x32_bf16 v[46:49], v[136:139], v[120:123], v[46:49]
	v_mfma_f32_16x16x32_bf16 v[58:61], v[140:143], v[120:123], v[58:61]
	v_mfma_f32_16x16x32_bf16 v[50:53], v[144:147], v[120:123], v[50:53]
	v_mfma_f32_16x16x32_bf16 v[42:45], v[132:135], v[124:127], v[42:45]
	v_mfma_f32_16x16x32_bf16 v[62:65], v[136:139], v[124:127], v[62:65]
	v_mfma_f32_16x16x32_bf16 v[68:71], v[140:143], v[124:127], v[68:71]
	v_mfma_f32_16x16x32_bf16 v[54:57], v[144:147], v[124:127], v[54:57]
	v_mfma_f32_16x16x32_bf16 v[34:37], v[132:135], v[128:131], v[34:37]
	v_mfma_f32_16x16x32_bf16 v[30:33], v[136:139], v[128:131], v[30:33]
	v_mfma_f32_16x16x32_bf16 v[26:29], v[140:143], v[128:131], v[26:29]
	v_mfma_f32_16x16x32_bf16 v[18:21], v[144:147], v[128:131], v[18:21]
	s_waitcnt vmcnt(6) lgkmcnt(0)
	s_barrier
	ds_read_b128 v[116:119], v8
	ds_read_b128 v[120:123], v8 offset:2048
	ds_read_b128 v[124:127], v8 offset:4096
	ds_read_b128 v[128:131], v8 offset:6144
	ds_read_b128 v[132:135], v9 offset:16384
	ds_read_b128 v[136:139], v9 offset:18432
	ds_read_b128 v[140:143], v9 offset:20480
	ds_read_b128 v[144:147], v9 offset:22528
	v_mfma_f32_16x16x32_bf16 v[80:83], v[100:103], v[72:75], v[80:83]
	v_mfma_f32_16x16x32_bf16 v[84:87], v[104:107], v[72:75], v[84:87]
	v_mfma_f32_16x16x32_bf16 v[88:91], v[108:111], v[72:75], v[88:91]
	v_mfma_f32_16x16x32_bf16 v[22:25], v[112:115], v[72:75], v[22:25]
	v_mfma_f32_16x16x32_bf16 v[38:41], v[100:103], v[76:79], v[38:41]
	v_mfma_f32_16x16x32_bf16 v[46:49], v[104:107], v[76:79], v[46:49]
	v_mfma_f32_16x16x32_bf16 v[58:61], v[108:111], v[76:79], v[58:61]
	v_mfma_f32_16x16x32_bf16 v[50:53], v[112:115], v[76:79], v[50:53]
	v_mfma_f32_16x16x32_bf16 v[42:45], v[100:103], v[92:95], v[42:45]
	v_mfma_f32_16x16x32_bf16 v[62:65], v[104:107], v[92:95], v[62:65]
	v_mfma_f32_16x16x32_bf16 v[68:71], v[108:111], v[92:95], v[68:71]
	v_mfma_f32_16x16x32_bf16 v[54:57], v[112:115], v[92:95], v[54:57]
	v_mfma_f32_16x16x32_bf16 v[34:37], v[100:103], v[96:99], v[34:37]
	v_mfma_f32_16x16x32_bf16 v[30:33], v[104:107], v[96:99], v[30:33]
	v_mfma_f32_16x16x32_bf16 v[26:29], v[108:111], v[96:99], v[26:29]
	v_mfma_f32_16x16x32_bf16 v[18:21], v[112:115], v[96:99], v[18:21]
	s_mov_b32 m0, s69
	v_lshl_add_u64 v[72:73], v[4:5], 0, s[34:35]
	global_load_lds_dwordx4 v[72:73], off
	v_lshl_add_u64 v[72:73], v[6:7], 0, s[34:35]
	s_mov_b32 m0, s70
	s_mov_b64 s[4:5], 0x4000700
	global_load_lds_dwordx4 v[72:73], off
	v_lshl_add_u64 v[72:73], v[2:3], 0, s[4:5]
	s_mov_b32 m0, s71
	s_mov_b64 s[4:5], 0x4020700
	global_load_lds_dwordx4 v[72:73], off
	v_lshl_add_u64 v[72:73], v[2:3], 0, s[4:5]
	s_mov_b32 m0, s72
	s_mov_b64 s[4:5], 0x4040700
	global_load_lds_dwordx4 v[72:73], off
	v_lshl_add_u64 v[72:73], v[2:3], 0, s[4:5]
	s_mov_b32 m0, s73
	s_mov_b64 s[4:5], 0x4060700
	global_load_lds_dwordx4 v[72:73], off
	v_lshl_add_u64 v[72:73], v[2:3], 0, s[4:5]
	s_mov_b32 m0, s74
	v_readlane_b32 s72, v197, 34
	global_load_lds_dwordx4 v[72:73], off
	ds_read_b128 v[72:75], v10
	ds_read_b128 v[76:79], v10 offset:2048
	ds_read_b128 v[92:95], v10 offset:4096
	ds_read_b128 v[96:99], v10 offset:6144
	ds_read_b128 v[100:103], v11 offset:16384
	ds_read_b128 v[104:107], v11 offset:18432
	ds_read_b128 v[108:111], v11 offset:20480
	ds_read_b128 v[112:115], v11 offset:22528
	v_readlane_b32 s73, v197, 35
	v_readlane_b32 s82, v197, 44
	v_readlane_b32 s83, v197, 45
	v_readlane_b32 s84, v197, 46
	v_readlane_b32 s85, v197, 47
	v_readlane_b32 s74, v197, 36
	v_readlane_b32 s75, v197, 37
	v_readlane_b32 s76, v197, 38
	v_readlane_b32 s77, v197, 39
	v_readlane_b32 s78, v197, 40
	v_readlane_b32 s79, v197, 41
	v_readlane_b32 s80, v197, 42
	v_readlane_b32 s81, v197, 43
	v_readlane_b32 s86, v197, 48
	v_readlane_b32 s87, v197, 49
	s_waitcnt lgkmcnt(8)
	v_mfma_f32_16x16x32_bf16 v[80:83], v[132:135], v[116:119], v[80:83]
	v_mfma_f32_16x16x32_bf16 v[84:87], v[136:139], v[116:119], v[84:87]
	v_mfma_f32_16x16x32_bf16 v[88:91], v[140:143], v[116:119], v[88:91]
	v_mfma_f32_16x16x32_bf16 v[22:25], v[144:147], v[116:119], v[22:25]
	v_mfma_f32_16x16x32_bf16 v[38:41], v[132:135], v[120:123], v[38:41]
	v_mfma_f32_16x16x32_bf16 v[46:49], v[136:139], v[120:123], v[46:49]
	v_mfma_f32_16x16x32_bf16 v[58:61], v[140:143], v[120:123], v[58:61]
	v_mfma_f32_16x16x32_bf16 v[50:53], v[144:147], v[120:123], v[50:53]
	v_mfma_f32_16x16x32_bf16 v[42:45], v[132:135], v[124:127], v[42:45]
	v_mfma_f32_16x16x32_bf16 v[62:65], v[136:139], v[124:127], v[62:65]
	v_mfma_f32_16x16x32_bf16 v[68:71], v[140:143], v[124:127], v[68:71]
	v_mfma_f32_16x16x32_bf16 v[54:57], v[144:147], v[124:127], v[54:57]
	v_mfma_f32_16x16x32_bf16 v[34:37], v[132:135], v[128:131], v[34:37]
	v_mfma_f32_16x16x32_bf16 v[30:33], v[136:139], v[128:131], v[30:33]
	v_mfma_f32_16x16x32_bf16 v[26:29], v[140:143], v[128:131], v[26:29]
	v_mfma_f32_16x16x32_bf16 v[18:21], v[144:147], v[128:131], v[18:21]
	s_waitcnt vmcnt(6) lgkmcnt(0)
	s_barrier
	ds_read_b128 v[116:119], v8 offset:49152
	ds_read_b128 v[120:123], v8 offset:51200
	ds_read_b128 v[124:127], v8 offset:53248
	ds_read_b128 v[128:131], v8 offset:55296
	ds_read_b128 v[132:135], v12
	ds_read_b128 v[136:139], v12 offset:2048
	ds_read_b128 v[140:143], v12 offset:4096
	ds_read_b128 v[144:147], v12 offset:6144
	v_mfma_f32_16x16x32_bf16 v[80:83], v[100:103], v[72:75], v[80:83]
	v_mfma_f32_16x16x32_bf16 v[84:87], v[104:107], v[72:75], v[84:87]
	v_mfma_f32_16x16x32_bf16 v[88:91], v[108:111], v[72:75], v[88:91]
	v_mfma_f32_16x16x32_bf16 v[22:25], v[112:115], v[72:75], v[22:25]
	v_mfma_f32_16x16x32_bf16 v[38:41], v[100:103], v[76:79], v[38:41]
	v_mfma_f32_16x16x32_bf16 v[46:49], v[104:107], v[76:79], v[46:49]
	v_mfma_f32_16x16x32_bf16 v[58:61], v[108:111], v[76:79], v[58:61]
	v_mfma_f32_16x16x32_bf16 v[50:53], v[112:115], v[76:79], v[50:53]
	v_mfma_f32_16x16x32_bf16 v[42:45], v[100:103], v[92:95], v[42:45]
	v_mfma_f32_16x16x32_bf16 v[62:65], v[104:107], v[92:95], v[62:65]
	v_mfma_f32_16x16x32_bf16 v[68:71], v[108:111], v[92:95], v[68:71]
	v_mfma_f32_16x16x32_bf16 v[54:57], v[112:115], v[92:95], v[54:57]
	v_mfma_f32_16x16x32_bf16 v[34:37], v[100:103], v[96:99], v[34:37]
	v_mfma_f32_16x16x32_bf16 v[30:33], v[104:107], v[96:99], v[30:33]
	v_mfma_f32_16x16x32_bf16 v[26:29], v[108:111], v[96:99], v[26:29]
	v_mfma_f32_16x16x32_bf16 v[18:21], v[112:115], v[96:99], v[18:21]
	s_mov_b32 m0, s64
	v_lshl_add_u64 v[4:5], v[4:5], 0, s[36:37]
	global_load_lds_dwordx4 v[4:5], off
	v_lshl_add_u64 v[4:5], v[6:7], 0, s[36:37]
	s_mov_b32 m0, s2
	s_mov_b64 s[4:5], 0x4060780
	global_load_lds_dwordx4 v[4:5], off
	v_lshl_add_u64 v[4:5], v[2:3], 0, s[16:17]
	s_mov_b32 m0, s33
	s_nop 0
	global_load_lds_dwordx4 v[4:5], off
	v_lshl_add_u64 v[4:5], v[2:3], 0, s[18:19]
	s_mov_b32 m0, s61
	s_nop 0
	global_load_lds_dwordx4 v[4:5], off
	v_lshl_add_u64 v[4:5], v[2:3], 0, s[20:21]
	s_mov_b32 m0, s62
	v_lshl_add_u64 v[2:3], v[2:3], 0, s[4:5]
	global_load_lds_dwordx4 v[4:5], off
	s_mov_b32 m0, s63
	s_nop 0
	global_load_lds_dwordx4 v[2:3], off
	ds_read_b128 v[2:5], v10 offset:49152
	ds_read_b128 v[72:75], v10 offset:51200
	ds_read_b128 v[76:79], v10 offset:53248
	ds_read_b128 v[92:95], v10 offset:55296
	ds_read_b128 v[96:99], v13
	ds_read_b128 v[100:103], v13 offset:2048
	ds_read_b128 v[104:107], v13 offset:4096
	ds_read_b128 v[108:111], v13 offset:6144
	s_waitcnt lgkmcnt(8)
	v_mfma_f32_16x16x32_bf16 v[80:83], v[132:135], v[116:119], v[80:83]
	v_mfma_f32_16x16x32_bf16 v[84:87], v[136:139], v[116:119], v[84:87]
	v_mfma_f32_16x16x32_bf16 v[88:91], v[140:143], v[116:119], v[88:91]
	v_mfma_f32_16x16x32_bf16 v[22:25], v[144:147], v[116:119], v[22:25]
	v_mfma_f32_16x16x32_bf16 v[38:41], v[132:135], v[120:123], v[38:41]
	v_mfma_f32_16x16x32_bf16 v[46:49], v[136:139], v[120:123], v[46:49]
	v_mfma_f32_16x16x32_bf16 v[58:61], v[140:143], v[120:123], v[58:61]
	v_mfma_f32_16x16x32_bf16 v[50:53], v[144:147], v[120:123], v[50:53]
	v_mfma_f32_16x16x32_bf16 v[42:45], v[132:135], v[124:127], v[42:45]
	v_mfma_f32_16x16x32_bf16 v[62:65], v[136:139], v[124:127], v[62:65]
	v_mfma_f32_16x16x32_bf16 v[68:71], v[140:143], v[124:127], v[68:71]
	v_mfma_f32_16x16x32_bf16 v[54:57], v[144:147], v[124:127], v[54:57]
	v_mfma_f32_16x16x32_bf16 v[34:37], v[132:135], v[128:131], v[34:37]
	v_mfma_f32_16x16x32_bf16 v[30:33], v[136:139], v[128:131], v[30:33]
	v_mfma_f32_16x16x32_bf16 v[26:29], v[140:143], v[128:131], v[26:29]
	v_mfma_f32_16x16x32_bf16 v[18:21], v[144:147], v[128:131], v[18:21]
	s_waitcnt vmcnt(6) lgkmcnt(0)
	s_barrier
	ds_read_b128 v[112:115], v14
	ds_read_b128 v[116:119], v14 offset:2048
	ds_read_b128 v[120:123], v14 offset:4096
	ds_read_b128 v[124:127], v14 offset:6144
	ds_read_b128 v[128:131], v15
	ds_read_b128 v[132:135], v15 offset:2048
	ds_read_b128 v[136:139], v15 offset:4096
	ds_read_b128 v[12:15], v15 offset:6144
	v_mfma_f32_16x16x32_bf16 v[80:83], v[96:99], v[2:5], v[80:83]
	v_mfma_f32_16x16x32_bf16 v[84:87], v[100:103], v[2:5], v[84:87]
	v_mfma_f32_16x16x32_bf16 v[88:91], v[104:107], v[2:5], v[88:91]
	v_mfma_f32_16x16x32_bf16 v[2:5], v[108:111], v[2:5], v[22:25]
	v_mfma_f32_16x16x32_bf16 v[22:25], v[96:99], v[72:75], v[38:41]
	v_mfma_f32_16x16x32_bf16 v[38:41], v[100:103], v[72:75], v[46:49]
	v_mfma_f32_16x16x32_bf16 v[46:49], v[104:107], v[72:75], v[58:61]
	v_mfma_f32_16x16x32_bf16 v[50:53], v[108:111], v[72:75], v[50:53]
	v_mfma_f32_16x16x32_bf16 v[42:45], v[96:99], v[76:79], v[42:45]
	v_mfma_f32_16x16x32_bf16 v[58:61], v[100:103], v[76:79], v[62:65]
	v_mfma_f32_16x16x32_bf16 v[62:65], v[104:107], v[76:79], v[68:71]
	v_mfma_f32_16x16x32_bf16 v[54:57], v[108:111], v[76:79], v[54:57]
	v_mfma_f32_16x16x32_bf16 v[34:37], v[96:99], v[92:95], v[34:37]
	v_mfma_f32_16x16x32_bf16 v[30:33], v[100:103], v[92:95], v[30:33]
	v_mfma_f32_16x16x32_bf16 v[26:29], v[104:107], v[92:95], v[26:29]
	v_mfma_f32_16x16x32_bf16 v[18:21], v[108:111], v[92:95], v[18:21]
	ds_read_b128 v[68:71], v16
	ds_read_b128 v[72:75], v16 offset:2048
	ds_read_b128 v[76:79], v16 offset:4096
	ds_read_b128 v[92:95], v16 offset:6144
	ds_read_b128 v[96:99], v17
	ds_read_b128 v[100:103], v17 offset:2048
	ds_read_b128 v[104:107], v17 offset:4096
	ds_read_b128 v[108:111], v17 offset:6144
	s_waitcnt lgkmcnt(8)
	v_mfma_f32_16x16x32_bf16 v[80:83], v[128:131], v[112:115], v[80:83]
	v_mfma_f32_16x16x32_bf16 v[84:87], v[132:135], v[112:115], v[84:87]
	v_mfma_f32_16x16x32_bf16 v[88:91], v[136:139], v[112:115], v[88:91]
	v_mfma_f32_16x16x32_bf16 v[2:5], v[12:15], v[112:115], v[2:5]
	v_mfma_f32_16x16x32_bf16 v[22:25], v[128:131], v[116:119], v[22:25]
	v_mfma_f32_16x16x32_bf16 v[38:41], v[132:135], v[116:119], v[38:41]
	v_mfma_f32_16x16x32_bf16 v[46:49], v[136:139], v[116:119], v[46:49]
	v_mfma_f32_16x16x32_bf16 v[50:53], v[12:15], v[116:119], v[50:53]
	v_mfma_f32_16x16x32_bf16 v[42:45], v[128:131], v[120:123], v[42:45]
	v_mfma_f32_16x16x32_bf16 v[58:61], v[132:135], v[120:123], v[58:61]
	v_mfma_f32_16x16x32_bf16 v[62:65], v[136:139], v[120:123], v[62:65]
	v_mfma_f32_16x16x32_bf16 v[54:57], v[12:15], v[120:123], v[54:57]
	v_mfma_f32_16x16x32_bf16 v[34:37], v[128:131], v[124:127], v[34:37]
	v_mfma_f32_16x16x32_bf16 v[30:33], v[132:135], v[124:127], v[30:33]
	v_mfma_f32_16x16x32_bf16 v[26:29], v[136:139], v[124:127], v[26:29]
	v_mfma_f32_16x16x32_bf16 v[12:15], v[12:15], v[124:127], v[18:21]
	s_waitcnt vmcnt(0) lgkmcnt(0)
	s_barrier
	s_nop 1
	ds_read_b128 v[16:19], v8
	ds_read_b128 v[112:115], v8 offset:2048
	ds_read_b128 v[116:119], v8 offset:4096
	ds_read_b128 v[120:123], v8 offset:6144
	ds_read_b128 v[124:127], v9 offset:16384
	ds_read_b128 v[128:131], v9 offset:18432
	ds_read_b128 v[132:135], v9 offset:20480
	ds_read_b128 v[6:9], v9 offset:22528
	v_mfma_f32_16x16x32_bf16 v[80:83], v[96:99], v[68:71], v[80:83]
	v_mfma_f32_16x16x32_bf16 v[84:87], v[100:103], v[68:71], v[84:87]
	v_mfma_f32_16x16x32_bf16 v[88:91], v[104:107], v[68:71], v[88:91]
	v_mfma_f32_16x16x32_bf16 v[2:5], v[108:111], v[68:71], v[2:5]
	v_mfma_f32_16x16x32_bf16 v[20:23], v[96:99], v[72:75], v[22:25]
	v_mfma_f32_16x16x32_bf16 v[38:41], v[100:103], v[72:75], v[38:41]
	v_mfma_f32_16x16x32_bf16 v[46:49], v[104:107], v[72:75], v[46:49]
	v_mfma_f32_16x16x32_bf16 v[50:53], v[108:111], v[72:75], v[50:53]
	v_mfma_f32_16x16x32_bf16 v[42:45], v[96:99], v[76:79], v[42:45]
	v_mfma_f32_16x16x32_bf16 v[58:61], v[100:103], v[76:79], v[58:61]
	v_mfma_f32_16x16x32_bf16 v[62:65], v[104:107], v[76:79], v[62:65]
	v_mfma_f32_16x16x32_bf16 v[54:57], v[108:111], v[76:79], v[54:57]
	v_mfma_f32_16x16x32_bf16 v[34:37], v[96:99], v[92:95], v[34:37]
	v_mfma_f32_16x16x32_bf16 v[30:33], v[100:103], v[92:95], v[30:33]
	v_mfma_f32_16x16x32_bf16 v[24:27], v[104:107], v[92:95], v[26:29]
	v_mfma_f32_16x16x32_bf16 v[12:15], v[108:111], v[92:95], v[12:15]
	ds_read_b128 v[68:71], v10
	ds_read_b128 v[72:75], v10 offset:2048
	ds_read_b128 v[76:79], v10 offset:4096
	ds_read_b128 v[92:95], v10 offset:6144
	ds_read_b128 v[96:99], v11 offset:16384
	ds_read_b128 v[100:103], v11 offset:18432
	ds_read_b128 v[104:107], v11 offset:20480
	ds_read_b128 v[108:111], v11 offset:22528
	s_waitcnt lgkmcnt(8)
	v_mfma_f32_16x16x32_bf16 v[80:83], v[124:127], v[16:19], v[80:83]
	v_mfma_f32_16x16x32_bf16 v[84:87], v[128:131], v[16:19], v[84:87]
	v_mfma_f32_16x16x32_bf16 v[88:91], v[132:135], v[16:19], v[88:91]
	v_mfma_f32_16x16x32_bf16 v[2:5], v[6:9], v[16:19], v[2:5]
	v_mfma_f32_16x16x32_bf16 v[16:19], v[124:127], v[112:115], v[20:23]
	v_mfma_f32_16x16x32_bf16 v[20:23], v[128:131], v[112:115], v[38:41]
	v_mfma_f32_16x16x32_bf16 v[38:41], v[132:135], v[112:115], v[46:49]
	v_mfma_f32_16x16x32_bf16 v[112:115], v[6:9], v[112:115], v[50:53]
	v_mfma_f32_16x16x32_bf16 v[136:139], v[124:127], v[116:119], v[42:45]
	v_mfma_f32_16x16x32_bf16 v[140:143], v[128:131], v[116:119], v[58:61]
	v_mfma_f32_16x16x32_bf16 v[144:147], v[132:135], v[116:119], v[62:65]
	v_mfma_f32_16x16x32_bf16 v[116:119], v[6:9], v[116:119], v[54:57]
	v_mfma_f32_16x16x32_bf16 v[124:127], v[124:127], v[120:123], v[34:37]
	v_mfma_f32_16x16x32_bf16 v[128:131], v[128:131], v[120:123], v[30:33]
	v_mfma_f32_16x16x32_bf16 v[132:135], v[132:135], v[120:123], v[24:27]
	v_mfma_f32_16x16x32_bf16 v[120:123], v[6:9], v[120:123], v[12:15]
	s_waitcnt vmcnt(0) lgkmcnt(0)
	s_barrier
	v_mfma_f32_16x16x32_bf16 v[58:61], v[96:99], v[68:71], v[80:83]
	v_mfma_f32_16x16x32_bf16 v[62:65], v[100:103], v[68:71], v[84:87]
	v_mfma_f32_16x16x32_bf16 v[54:57], v[104:107], v[68:71], v[88:91]
	v_mfma_f32_16x16x32_bf16 v[50:53], v[108:111], v[68:71], v[2:5]
	v_mfma_f32_16x16x32_bf16 v[42:45], v[96:99], v[72:75], v[16:19]
	v_mfma_f32_16x16x32_bf16 v[46:49], v[100:103], v[72:75], v[20:23]
	v_mfma_f32_16x16x32_bf16 v[38:41], v[104:107], v[72:75], v[38:41]
	v_mfma_f32_16x16x32_bf16 v[34:37], v[108:111], v[72:75], v[112:115]
	v_mfma_f32_16x16x32_bf16 v[26:29], v[96:99], v[76:79], v[136:139]
	v_mfma_f32_16x16x32_bf16 v[30:33], v[100:103], v[76:79], v[140:143]
	v_mfma_f32_16x16x32_bf16 v[22:25], v[104:107], v[76:79], v[144:147]
	v_mfma_f32_16x16x32_bf16 v[18:21], v[108:111], v[76:79], v[116:119]
	v_mfma_f32_16x16x32_bf16 v[10:13], v[96:99], v[92:95], v[124:127]
	v_mfma_f32_16x16x32_bf16 v[14:17], v[100:103], v[92:95], v[128:131]
	v_mfma_f32_16x16x32_bf16 v[6:9], v[104:107], v[92:95], v[132:135]
	v_mfma_f32_16x16x32_bf16 v[2:5], v[108:111], v[92:95], v[120:123]
	v_ashrrev_i32_e32 v66, 2, v1
	v_and_b32_e32 v66, 0xffffffc0, v66
	v_add_u32_e32 v66, s59, v66
	v_and_or_b32 v68, v1, 15, v66
	v_mul_f32_e32 v66, 0xbfb8aa3b, v58
	v_exp_f32_e32 v72, v66
	v_mul_f32_e32 v66, 0xbfb8aa3b, v59
	v_exp_f32_e32 v73, v66
	s_ashr_i32 s59, s58, 31
	s_lshl_b64 s[4:5], s[58:59], 20
	v_lshrrev_b32_e32 v78, 1, v1
	v_pk_add_f32 v[76:77], v[72:73], 1.0 op_sel_hi:[1,0]
	v_ashrrev_i32_e32 v69, 31, v68
	s_add_u32 s4, s22, s4
	v_and_b32_e32 v66, 0xc0, v1
	v_div_scale_f32 v1, s[58:59], v77, v77, v59
	s_addc_u32 s5, s23, s5
	v_lshlrev_b64 v[70:71], 11, v[68:69]
	v_rcp_f32_e32 v69, v1
	v_lshl_add_u64 v[70:71], s[4:5], 0, v[70:71]
	s_lshl_b32 s2, s60, 8
	v_lshl_add_u64 v[70:71], v[70:71], 0, s[2:3]
	v_lshl_add_u64 v[74:75], v[70:71], 0, v[66:67]
	v_and_b32_e32 v70, 24, v78
	v_mov_b32_e32 v71, v67
	v_lshl_add_u64 v[72:73], v[74:75], 0, v[70:71]
	v_fma_f32 v74, -v1, v69, 1.0
	v_fmac_f32_e32 v69, v74, v69
	v_div_scale_f32 v74, vcc, v59, v77, v59
	v_mul_f32_e32 v75, v74, v69
	v_fma_f32 v78, -v1, v75, v74
	v_fmac_f32_e32 v75, v78, v69
	v_div_scale_f32 v78, s[58:59], v76, v76, v58
	v_rcp_f32_e32 v79, v78
	v_fma_f32 v1, -v1, v75, v74
	v_div_fmas_f32 v1, v1, v69, v75
	v_mul_f32_e32 v74, 0xbfb8aa3b, v60
	v_mul_f32_e32 v75, 0xbfb8aa3b, v61
	v_exp_f32_e32 v74, v74
	v_exp_f32_e32 v75, v75
	v_div_fixup_f32 v59, v1, v77, v59
	v_fma_f32 v1, -v78, v79, 1.0
	v_fmac_f32_e32 v79, v1, v79
	v_div_scale_f32 v1, vcc, v58, v76, v58
	v_mul_f32_e32 v69, v1, v79
	v_fma_f32 v77, -v78, v69, v1
	v_pk_add_f32 v[74:75], v[74:75], 1.0 op_sel_hi:[1,0]
	v_fmac_f32_e32 v69, v77, v79
	v_div_scale_f32 v77, s[58:59], v75, v75, v61
	v_fma_f32 v1, -v78, v69, v1
	v_rcp_f32_e32 v78, v77
	v_div_fmas_f32 v1, v1, v79, v69
	v_div_fixup_f32 v58, v1, v76, v58
	v_pk_mul_f32 v[58:59], v[62:63], v[58:59]
	v_fma_f32 v1, -v77, v78, 1.0
	v_fmac_f32_e32 v78, v1, v78
	v_div_scale_f32 v1, vcc, v61, v75, v61
	v_mul_f32_e32 v62, v1, v78
	v_fma_f32 v63, -v77, v62, v1
	v_fmac_f32_e32 v62, v63, v78
	v_div_scale_f32 v63, s[58:59], v74, v74, v60
	v_rcp_f32_e32 v69, v63
	v_fma_f32 v1, -v77, v62, v1
	v_div_fmas_f32 v1, v1, v78, v62
	v_div_fixup_f32 v61, v1, v75, v61
	v_fma_f32 v1, -v63, v69, 1.0
	v_fmac_f32_e32 v69, v1, v69
	v_div_scale_f32 v1, vcc, v60, v74, v60
	v_mul_f32_e32 v75, v1, v69
	v_fma_f32 v62, -v63, v75, v1
	v_fmac_f32_e32 v75, v62, v69
	v_fma_f32 v1, -v63, v75, v1
	v_mul_f32_e32 v62, 0xbfb8aa3b, v54
	v_mul_f32_e32 v63, 0xbfb8aa3b, v55
	v_exp_f32_e32 v62, v62
	v_exp_f32_e32 v63, v63
	v_div_fmas_f32 v1, v1, v69, v75
	v_div_fixup_f32 v60, v1, v74, v60
	v_pk_mul_f32 v[60:61], v[64:65], v[60:61]
	v_pk_add_f32 v[62:63], v[62:63], 1.0 op_sel_hi:[1,0]
	v_cvt_pk_bf16_f32 v58, v58, v59
	v_div_scale_f32 v1, s[58:59], v63, v63, v55
	v_rcp_f32_e32 v64, v1
	v_cvt_pk_bf16_f32 v59, v60, v61
	s_waitcnt lgkmcnt(0)
	s_barrier
	s_mov_b32 s99, 0
	s_lshr_b32 s57, s39, 7
	s_add_i32 s57, s98, s57
	s_cmpk_ge_i32 s57, 0x800
	s_cbranch_scc1 .Lpf15_p2_skip
	s_mov_b32 s60, s57
	s_cmp_lg_u32 s39, 0x8000
	s_cbranch_scc1 .Lpf15_p2_nomap
	s_lshr_b32 s32, s57, 8
	s_bfe_u32 s33, s57, 0x30005
	s_and_b32 s58, s57, 31
	s_lshr_b32 s59, s32, 2
	s_lshl_b32 s59, s59, 3
	s_add_i32 s33, s33, s59
	s_and_b32 s32, s32, 3
	s_lshr_b32 s59, s32, 1
	s_xor_b32 s32, s32, s59
	s_and_b32 s32, s32, 1
	s_lshl_b32 s59, s59, 3
	s_lshr_b32 s61, s58, 2
	s_add_i32 s59, s59, s61
	s_and_b32 s58, s58, 3
	s_lshl_b32 s32, s32, 2
	s_add_i32 s32, s32, s58
	s_lshl_b32 s33, s33, 7
	s_lshl_b32 s32, s32, 4
	s_add_i32 s33, s33, s32
	s_add_i32 s60, s33, s59
.Lpf15_p2_nomap:
	s_ashr_i32 s32, s60, 7
	s_ashr_i32 s33, s32, 31
	s_lshl_b64 s[32:33], s[32:33], 22
	s_add_u32 s32, s82, s32
	s_addc_u32 s33, s83, s33
	s_bfe_u32 s58, s60, 0x30004
	s_lshl_b32 s58, s58, 19
	s_add_u32 s32, s32, s58
	s_addc_u32 s33, s33, 0
	s_bfe_u32 s58, s60, 0x20002
	s_lshl_b32 s58, s58, 12
	s_mov_b32 s59, 0
	v_ashrrev_i32_e32 v202, 3, v0
	v_lshrrev_b32_e32 v206, 4, v0
	v_xor_b32_e32 v206, v206, v0
	v_lshlrev_b32_e32 v206, 4, v206
	v_and_b32_e32 v206, 0x70, v206
	v_mov_b32_e32 v207, 0
	v_ashrrev_i32_e32 v203, 31, v202
	v_lshlrev_b64 v[202:203], 11, v[202:203]
	v_lshl_add_u64 v[202:203], s[32:33], 0, v[202:203]
	v_lshl_add_u64 v[202:203], v[202:203], 0, v[206:207]
	v_mov_b32_e32 v208, v200
	v_ashrrev_i32_e32 v209, 31, v200
	v_mov_b32_e32 v210, v201
	v_ashrrev_i32_e32 v211, 31, v201
	v_lshl_add_u64 v[208:209], v[208:209], 0, s[58:59]
	v_lshl_add_u64 v[210:211], v[210:211], 0, s[58:59]
	v_lshlrev_b64 v[208:209], 11, v[208:209]
	v_lshlrev_b64 v[210:211], 11, v[210:211]
	v_lshl_add_u64 v[208:209], s[8:9], 0, v[208:209]
	v_lshl_add_u64 v[210:211], s[8:9], 0, v[210:211]
	v_lshl_add_u64 v[208:209], v[208:209], 0, v[206:207]
	v_lshl_add_u64 v[210:211], v[210:211], 0, v[206:207]
	v_readfirstlane_b32 s61, v0
	s_nop 3
	s_lshl_b32 s61, s61, 4
	s_and_b32 s61, s61, 0xfffffc00
	s_mov_b64 s[32:33], 0x4000000
	v_lshl_add_u64 v[230:231], v[202:203], 0, s[32:33]
	s_mov_b64 s[32:33], 0x4020000
	v_lshl_add_u64 v[212:213], v[202:203], 0, s[32:33]
	s_mov_b64 s[32:33], 0x4040000
	v_lshl_add_u64 v[214:215], v[202:203], 0, s[32:33]
	s_mov_b64 s[32:33], 0x4060000
	v_lshl_add_u64 v[216:217], v[202:203], 0, s[32:33]
	s_mov_b64 s[32:33], 0x80
	v_lshl_add_u64 v[218:219], v[208:209], 0, s[32:33]
	s_mov_b64 s[32:33], 0x80
	v_lshl_add_u64 v[220:221], v[210:211], 0, s[32:33]
	s_mov_b64 s[32:33], 0x4000080
	v_lshl_add_u64 v[222:223], v[202:203], 0, s[32:33]
	s_mov_b64 s[32:33], 0x4020080
	v_lshl_add_u64 v[224:225], v[202:203], 0, s[32:33]
	s_mov_b64 s[32:33], 0x4040080
	v_lshl_add_u64 v[226:227], v[202:203], 0, s[32:33]
	s_mov_b64 s[32:33], 0x4060080
	v_lshl_add_u64 v[228:229], v[202:203], 0, s[32:33]
	s_mov_b32 s62, s61
	s_mov_b32 s99, 1
.Lpf15_p2_skip:
	global_store_dwordx2 v[72:73], v[58:59], off
	v_fma_f32 v58, -v1, v64, 1.0
	v_fmac_f32_e32 v64, v58, v64
	v_div_scale_f32 v58, vcc, v55, v63, v55
	v_mul_f32_e32 v59, v58, v64
	v_fma_f32 v60, -v1, v59, v58
	v_fmac_f32_e32 v59, v60, v64
	v_div_scale_f32 v60, s[58:59], v62, v62, v54
	v_rcp_f32_e32 v61, v60
	v_fma_f32 v1, -v1, v59, v58
	v_div_fmas_f32 v1, v1, v64, v59
	v_mul_f32_e32 v58, 0xbfb8aa3b, v56
	v_mul_f32_e32 v59, 0xbfb8aa3b, v57
	v_div_fixup_f32 v55, v1, v63, v55
	v_fma_f32 v1, -v60, v61, 1.0
	v_exp_f32_e32 v58, v58
	v_exp_f32_e32 v59, v59
	s_cmp_eq_u32 s99, 1
	s_cbranch_scc0 .Lpf15_sp0
	s_mov_b32 m0, s62
	s_nop 0
	global_load_lds_dwordx4 v[208:209], off
.Lpf15_sp0:
	v_fmac_f32_e32 v61, v1, v61
	v_div_scale_f32 v1, vcc, v54, v62, v54
	v_mul_f32_e32 v63, v1, v61
	v_fma_f32 v64, -v60, v63, v1
	v_fmac_f32_e32 v63, v64, v61
	v_pk_add_f32 v[58:59], v[58:59], 1.0 op_sel_hi:[1,0]
	v_fma_f32 v1, -v60, v63, v1
	v_div_scale_f32 v60, s[58:59], v59, v59, v57
	v_rcp_f32_e32 v64, v60
	v_div_fmas_f32 v1, v1, v61, v63
	v_div_fixup_f32 v54, v1, v62, v54
	v_pk_mul_f32 v[50:51], v[50:51], v[54:55]
	v_fma_f32 v1, -v60, v64, 1.0
	v_fmac_f32_e32 v64, v1, v64
	v_div_scale_f32 v1, vcc, v57, v59, v57
	v_mul_f32_e32 v54, v1, v64
	v_fma_f32 v55, -v60, v54, v1
	v_fmac_f32_e32 v54, v55, v64
	v_fma_f32 v1, -v60, v54, v1
	v_div_scale_f32 v60, s[58:59], v58, v58, v56
	v_rcp_f32_e32 v61, v60
	v_div_fmas_f32 v1, v1, v64, v54
	v_div_fixup_f32 v55, v1, v59, v57
	v_cvt_pk_bf16_f32 v50, v50, v51
	v_fma_f32 v1, -v60, v61, 1.0
	v_fmac_f32_e32 v61, v1, v61
	v_div_scale_f32 v1, vcc, v56, v58, v56
	v_mul_f32_e32 v54, v1, v61
	v_fma_f32 v57, -v60, v54, v1
	v_fmac_f32_e32 v54, v57, v61
	v_fma_f32 v1, -v60, v54, v1
	v_div_fmas_f32 v1, v1, v61, v54
	v_div_fixup_f32 v54, v1, v58, v56
	v_pk_mul_f32 v[52:53], v[52:53], v[54:55]
	v_mul_f32_e32 v1, 0xbfb8aa3b, v42
	v_cvt_pk_bf16_f32 v51, v52, v53
	s_cmp_eq_u32 s99, 1
	s_cbranch_scc0 .Lpf15_sp1
	s_add_i32 m0, s62, 0x2000
	s_nop 0
	global_load_lds_dwordx4 v[210:211], off
.Lpf15_sp1:
	v_exp_f32_e32 v52, v1
	v_mul_f32_e32 v1, 0xbfb8aa3b, v43
	v_exp_f32_e32 v53, v1
	global_store_dwordx2 v[72:73], v[50:51], off offset:32
	v_or_b32_e32 v50, 16, v68
	v_ashrrev_i32_e32 v51, 31, v50
	v_pk_add_f32 v[52:53], v[52:53], 1.0 op_sel_hi:[1,0]
	v_lshlrev_b64 v[50:51], 11, v[50:51]
	v_div_scale_f32 v1, s[58:59], v53, v53, v43
	v_rcp_f32_e32 v54, v1
	v_lshl_add_u64 v[50:51], s[4:5], 0, v[50:51]
	v_lshl_add_u64 v[50:51], v[50:51], 0, s[2:3]
	v_lshl_add_u64 v[50:51], v[50:51], 0, v[66:67]
	v_fma_f32 v55, -v1, v54, 1.0
	v_fmac_f32_e32 v54, v55, v54
	v_div_scale_f32 v55, vcc, v43, v53, v43
	v_mul_f32_e32 v56, v55, v54
	v_fma_f32 v57, -v1, v56, v55
	v_fmac_f32_e32 v56, v57, v54
	v_div_scale_f32 v57, s[58:59], v52, v52, v42
	v_rcp_f32_e32 v58, v57
	v_fma_f32 v1, -v1, v56, v55
	v_div_fmas_f32 v1, v1, v54, v56
	v_mul_f32_e32 v54, 0xbfb8aa3b, v44
	v_mul_f32_e32 v55, 0xbfb8aa3b, v45
	v_exp_f32_e32 v54, v54
	v_exp_f32_e32 v55, v55
	v_div_fixup_f32 v43, v1, v53, v43
	v_fma_f32 v1, -v57, v58, 1.0
	v_fmac_f32_e32 v58, v1, v58
	v_div_scale_f32 v1, vcc, v42, v52, v42
	v_mul_f32_e32 v53, v1, v58
	v_fma_f32 v56, -v57, v53, v1
	v_pk_add_f32 v[54:55], v[54:55], 1.0 op_sel_hi:[1,0]
	v_fmac_f32_e32 v53, v56, v58
	v_div_scale_f32 v56, s[58:59], v55, v55, v45
	s_cmp_eq_u32 s99, 1
	s_cbranch_scc0 .Lpf15_sp2
	s_add_i32 m0, s62, 0x4000
	s_nop 0
	global_load_lds_dwordx4 v[230:231], off
.Lpf15_sp2:
	v_fma_f32 v1, -v57, v53, v1
	v_rcp_f32_e32 v57, v56
	v_div_fmas_f32 v1, v1, v58, v53
	v_div_fixup_f32 v42, v1, v52, v42
	v_pk_mul_f32 v[42:43], v[46:47], v[42:43]
	v_fma_f32 v1, -v56, v57, 1.0
	v_fmac_f32_e32 v57, v1, v57
	v_div_scale_f32 v1, vcc, v45, v55, v45
	v_mul_f32_e32 v46, v1, v57
	v_fma_f32 v47, -v56, v46, v1
	v_fmac_f32_e32 v46, v47, v57
	v_div_scale_f32 v47, s[58:59], v54, v54, v44
	v_rcp_f32_e32 v52, v47
	v_fma_f32 v1, -v56, v46, v1
	v_div_fmas_f32 v1, v1, v57, v46
	v_div_fixup_f32 v45, v1, v55, v45
	v_fma_f32 v1, -v47, v52, 1.0
	v_fmac_f32_e32 v52, v1, v52
	v_div_scale_f32 v1, vcc, v44, v54, v44
	v_mul_f32_e32 v53, v1, v52
	v_fma_f32 v46, -v47, v53, v1
	v_fmac_f32_e32 v53, v46, v52
	v_fma_f32 v1, -v47, v53, v1
	v_mul_f32_e32 v46, 0xbfb8aa3b, v38
	v_mul_f32_e32 v47, 0xbfb8aa3b, v39
	v_exp_f32_e32 v46, v46
	v_exp_f32_e32 v47, v47
	v_div_fmas_f32 v1, v1, v52, v53
	v_div_fixup_f32 v44, v1, v54, v44
	v_pk_mul_f32 v[44:45], v[48:49], v[44:45]
	v_pk_add_f32 v[46:47], v[46:47], 1.0 op_sel_hi:[1,0]
	v_lshl_add_u64 v[50:51], v[50:51], 0, v[70:71]
	v_div_scale_f32 v1, s[58:59], v47, v47, v39
	v_rcp_f32_e32 v48, v1
	v_cvt_pk_bf16_f32 v42, v42, v43
	v_cvt_pk_bf16_f32 v43, v44, v45
	s_cmp_eq_u32 s99, 1
	s_cbranch_scc0 .Lpf15_sp3
	s_add_i32 m0, s62, 0x6000
	s_nop 0
	global_load_lds_dwordx4 v[212:213], off
.Lpf15_sp3:
	global_store_dwordx2 v[50:51], v[42:43], off
	v_fma_f32 v42, -v1, v48, 1.0
	v_fmac_f32_e32 v48, v42, v48
	v_div_scale_f32 v42, vcc, v39, v47, v39
	v_mul_f32_e32 v43, v42, v48
	v_fma_f32 v44, -v1, v43, v42
	v_fmac_f32_e32 v43, v44, v48
	v_div_scale_f32 v44, s[58:59], v46, v46, v38
	v_rcp_f32_e32 v45, v44
	v_fma_f32 v1, -v1, v43, v42
	v_div_fmas_f32 v1, v1, v48, v43
	v_mul_f32_e32 v42, 0xbfb8aa3b, v40
	v_mul_f32_e32 v43, 0xbfb8aa3b, v41
	v_div_fixup_f32 v39, v1, v47, v39
	v_fma_f32 v1, -v44, v45, 1.0
	v_exp_f32_e32 v42, v42
	v_exp_f32_e32 v43, v43
	v_fmac_f32_e32 v45, v1, v45
	v_div_scale_f32 v1, vcc, v38, v46, v38
	v_mul_f32_e32 v47, v1, v45
	v_fma_f32 v48, -v44, v47, v1
	v_fmac_f32_e32 v47, v48, v45
	v_pk_add_f32 v[42:43], v[42:43], 1.0 op_sel_hi:[1,0]
	v_fma_f32 v1, -v44, v47, v1
	v_div_scale_f32 v44, s[58:59], v43, v43, v41
	v_rcp_f32_e32 v48, v44
	v_div_fmas_f32 v1, v1, v45, v47
	v_div_fixup_f32 v38, v1, v46, v38
	v_pk_mul_f32 v[34:35], v[34:35], v[38:39]
	v_fma_f32 v1, -v44, v48, 1.0
	v_fmac_f32_e32 v48, v1, v48
	v_div_scale_f32 v1, vcc, v41, v43, v41
	v_mul_f32_e32 v38, v1, v48
	v_fma_f32 v39, -v44, v38, v1
	v_fmac_f32_e32 v38, v39, v48
	v_fma_f32 v1, -v44, v38, v1
	s_cmp_eq_u32 s99, 1
	s_cbranch_scc0 .Lpf15_sp4
	s_add_i32 m0, s62, 0x8000
	s_nop 0
	global_load_lds_dwordx4 v[214:215], off
.Lpf15_sp4:
	v_div_scale_f32 v44, s[58:59], v42, v42, v40
	v_rcp_f32_e32 v45, v44
	v_div_fmas_f32 v1, v1, v48, v38
	v_div_fixup_f32 v39, v1, v43, v41
	v_cvt_pk_bf16_f32 v34, v34, v35
	v_fma_f32 v1, -v44, v45, 1.0
	v_fmac_f32_e32 v45, v1, v45
	v_div_scale_f32 v1, vcc, v40, v42, v40
	v_mul_f32_e32 v38, v1, v45
	v_fma_f32 v41, -v44, v38, v1
	v_fmac_f32_e32 v38, v41, v45
	v_fma_f32 v1, -v44, v38, v1
	v_div_fmas_f32 v1, v1, v45, v38
	v_div_fixup_f32 v38, v1, v42, v40
	v_pk_mul_f32 v[36:37], v[36:37], v[38:39]
	v_mul_f32_e32 v1, 0xbfb8aa3b, v26
	v_cvt_pk_bf16_f32 v35, v36, v37
	v_exp_f32_e32 v36, v1
	v_mul_f32_e32 v1, 0xbfb8aa3b, v27
	v_exp_f32_e32 v37, v1
	global_store_dwordx2 v[50:51], v[34:35], off offset:32
	v_or_b32_e32 v34, 32, v68
	v_ashrrev_i32_e32 v35, 31, v34
	v_pk_add_f32 v[36:37], v[36:37], 1.0 op_sel_hi:[1,0]
	v_lshlrev_b64 v[34:35], 11, v[34:35]
	v_div_scale_f32 v1, s[58:59], v37, v37, v27
	v_rcp_f32_e32 v38, v1
	v_lshl_add_u64 v[34:35], s[4:5], 0, v[34:35]
	v_lshl_add_u64 v[34:35], v[34:35], 0, s[2:3]
	v_lshl_add_u64 v[34:35], v[34:35], 0, v[66:67]
	v_fma_f32 v39, -v1, v38, 1.0
	v_fmac_f32_e32 v38, v39, v38
	v_div_scale_f32 v39, vcc, v27, v37, v27
	v_mul_f32_e32 v40, v39, v38
	v_fma_f32 v41, -v1, v40, v39
	v_fmac_f32_e32 v40, v41, v38
	s_cmp_eq_u32 s99, 1
	s_cbranch_scc0 .Lpf15_sp5
	s_add_i32 m0, s62, 0xa000
	s_nop 0
	global_load_lds_dwordx4 v[216:217], off
.Lpf15_sp5:
	v_div_scale_f32 v41, s[58:59], v36, v36, v26
	v_rcp_f32_e32 v42, v41
	v_fma_f32 v1, -v1, v40, v39
	v_div_fmas_f32 v1, v1, v38, v40
	v_mul_f32_e32 v38, 0xbfb8aa3b, v28
	v_mul_f32_e32 v39, 0xbfb8aa3b, v29
	v_exp_f32_e32 v38, v38
	v_exp_f32_e32 v39, v39
	v_div_fixup_f32 v27, v1, v37, v27
	v_fma_f32 v1, -v41, v42, 1.0
	v_fmac_f32_e32 v42, v1, v42
	v_div_scale_f32 v1, vcc, v26, v36, v26
	v_mul_f32_e32 v37, v1, v42
	v_fma_f32 v40, -v41, v37, v1
	v_pk_add_f32 v[38:39], v[38:39], 1.0 op_sel_hi:[1,0]
	v_fmac_f32_e32 v37, v40, v42
	v_div_scale_f32 v40, s[58:59], v39, v39, v29
	v_fma_f32 v1, -v41, v37, v1
	v_rcp_f32_e32 v41, v40
	v_div_fmas_f32 v1, v1, v42, v37
	v_div_fixup_f32 v26, v1, v36, v26
	v_pk_mul_f32 v[26:27], v[30:31], v[26:27]
	v_fma_f32 v1, -v40, v41, 1.0
	v_fmac_f32_e32 v41, v1, v41
	v_div_scale_f32 v1, vcc, v29, v39, v29
	v_mul_f32_e32 v30, v1, v41
	v_fma_f32 v31, -v40, v30, v1
	v_fmac_f32_e32 v30, v31, v41
	v_div_scale_f32 v31, s[58:59], v38, v38, v28
	v_rcp_f32_e32 v36, v31
	v_fma_f32 v1, -v40, v30, v1
	v_div_fmas_f32 v1, v1, v41, v30
	v_div_fixup_f32 v29, v1, v39, v29
	v_fma_f32 v1, -v31, v36, 1.0
	v_fmac_f32_e32 v36, v1, v36
	v_div_scale_f32 v1, vcc, v28, v38, v28
	s_cmp_eq_u32 s99, 1
	s_cbranch_scc0 .Lpf15_sp6
	s_add_i32 m0, s62, 0xc000
	s_nop 0
	global_load_lds_dwordx4 v[218:219], off
.Lpf15_sp6:
	v_mul_f32_e32 v37, v1, v36
	v_fma_f32 v30, -v31, v37, v1
	v_fmac_f32_e32 v37, v30, v36
	v_fma_f32 v1, -v31, v37, v1
	v_mul_f32_e32 v30, 0xbfb8aa3b, v22
	v_mul_f32_e32 v31, 0xbfb8aa3b, v23
	v_exp_f32_e32 v30, v30
	v_exp_f32_e32 v31, v31
	v_div_fmas_f32 v1, v1, v36, v37
	v_div_fixup_f32 v28, v1, v38, v28
	v_pk_mul_f32 v[28:29], v[32:33], v[28:29]
	v_pk_add_f32 v[30:31], v[30:31], 1.0 op_sel_hi:[1,0]
	v_lshl_add_u64 v[34:35], v[34:35], 0, v[70:71]
	v_div_scale_f32 v1, s[58:59], v31, v31, v23
	v_rcp_f32_e32 v32, v1
	v_cvt_pk_bf16_f32 v26, v26, v27
	v_cvt_pk_bf16_f32 v27, v28, v29
	global_store_dwordx2 v[34:35], v[26:27], off
	v_fma_f32 v26, -v1, v32, 1.0
	v_fmac_f32_e32 v32, v26, v32
	v_div_scale_f32 v26, vcc, v23, v31, v23
	v_mul_f32_e32 v27, v26, v32
	v_fma_f32 v28, -v1, v27, v26
	v_fmac_f32_e32 v27, v28, v32
	v_div_scale_f32 v28, s[58:59], v30, v30, v22
	v_rcp_f32_e32 v29, v28
	v_fma_f32 v1, -v1, v27, v26
	v_div_fmas_f32 v1, v1, v32, v27
	v_mul_f32_e32 v26, 0xbfb8aa3b, v24
	v_mul_f32_e32 v27, 0xbfb8aa3b, v25
	v_div_fixup_f32 v23, v1, v31, v23
	v_fma_f32 v1, -v28, v29, 1.0
	v_exp_f32_e32 v26, v26
	v_exp_f32_e32 v27, v27
	v_fmac_f32_e32 v29, v1, v29
	v_div_scale_f32 v1, vcc, v22, v30, v22
	s_cmp_eq_u32 s99, 1
	s_cbranch_scc0 .Lpf15_sp7
	s_add_i32 m0, s62, 0xe000
	s_nop 0
	global_load_lds_dwordx4 v[220:221], off
.Lpf15_sp7:
	v_mul_f32_e32 v31, v1, v29
	v_fma_f32 v32, -v28, v31, v1
	v_fmac_f32_e32 v31, v32, v29
	v_pk_add_f32 v[26:27], v[26:27], 1.0 op_sel_hi:[1,0]
	v_fma_f32 v1, -v28, v31, v1
	v_div_scale_f32 v28, s[58:59], v27, v27, v25
	v_rcp_f32_e32 v32, v28
	v_div_fmas_f32 v1, v1, v29, v31
	v_div_fixup_f32 v22, v1, v30, v22
	v_pk_mul_f32 v[18:19], v[18:19], v[22:23]
	v_fma_f32 v1, -v28, v32, 1.0
	v_fmac_f32_e32 v32, v1, v32
	v_div_scale_f32 v1, vcc, v25, v27, v25
	v_mul_f32_e32 v22, v1, v32
	v_fma_f32 v23, -v28, v22, v1
	v_fmac_f32_e32 v22, v23, v32
	v_fma_f32 v1, -v28, v22, v1
	v_div_scale_f32 v28, s[58:59], v26, v26, v24
	v_rcp_f32_e32 v29, v28
	v_div_fmas_f32 v1, v1, v32, v22
	v_div_fixup_f32 v23, v1, v27, v25
	v_cvt_pk_bf16_f32 v18, v18, v19
	v_fma_f32 v1, -v28, v29, 1.0
	v_fmac_f32_e32 v29, v1, v29
	v_div_scale_f32 v1, vcc, v24, v26, v24
	v_mul_f32_e32 v22, v1, v29
	v_fma_f32 v25, -v28, v22, v1
	v_fmac_f32_e32 v22, v25, v29
	v_fma_f32 v1, -v28, v22, v1
	v_div_fmas_f32 v1, v1, v29, v22
	v_div_fixup_f32 v22, v1, v26, v24
	v_pk_mul_f32 v[20:21], v[20:21], v[22:23]
	v_mul_f32_e32 v1, 0xbfb8aa3b, v10
	v_cvt_pk_bf16_f32 v19, v20, v21
	v_exp_f32_e32 v20, v1
	v_mul_f32_e32 v1, 0xbfb8aa3b, v11
	s_cmp_eq_u32 s99, 1
	s_cbranch_scc0 .Lpf15_sp8
	s_add_i32 m0, s62, 0x10000
	s_nop 0
	global_load_lds_dwordx4 v[222:223], off
.Lpf15_sp8:
	v_exp_f32_e32 v21, v1
	global_store_dwordx2 v[34:35], v[18:19], off offset:32
	v_or_b32_e32 v18, 48, v68
	v_ashrrev_i32_e32 v19, 31, v18
	v_lshlrev_b64 v[18:19], 11, v[18:19]
	v_pk_add_f32 v[20:21], v[20:21], 1.0 op_sel_hi:[1,0]
	v_lshl_add_u64 v[18:19], s[4:5], 0, v[18:19]
	v_div_scale_f32 v1, s[4:5], v21, v21, v11
	v_rcp_f32_e32 v22, v1
	v_lshl_add_u64 v[18:19], v[18:19], 0, s[2:3]
	v_lshl_add_u64 v[18:19], v[18:19], 0, v[66:67]
	v_lshl_add_u64 v[18:19], v[18:19], 0, v[70:71]
	v_fma_f32 v23, -v1, v22, 1.0
	v_fmac_f32_e32 v22, v23, v22
	v_div_scale_f32 v23, vcc, v11, v21, v11
	v_mul_f32_e32 v24, v23, v22
	v_fma_f32 v25, -v1, v24, v23
	v_fmac_f32_e32 v24, v25, v22
	v_div_scale_f32 v25, s[4:5], v20, v20, v10
	v_rcp_f32_e32 v26, v25
	v_fma_f32 v1, -v1, v24, v23
	v_div_fmas_f32 v1, v1, v22, v24
	v_mul_f32_e32 v22, 0xbfb8aa3b, v12
	v_mul_f32_e32 v23, 0xbfb8aa3b, v13
	v_exp_f32_e32 v22, v22
	v_exp_f32_e32 v23, v23
	v_div_fixup_f32 v11, v1, v21, v11
	v_fma_f32 v1, -v25, v26, 1.0
	v_fmac_f32_e32 v26, v1, v26
	v_div_scale_f32 v1, vcc, v10, v20, v10
	v_mul_f32_e32 v21, v1, v26
	v_fma_f32 v24, -v25, v21, v1
	v_pk_add_f32 v[22:23], v[22:23], 1.0 op_sel_hi:[1,0]
	v_fmac_f32_e32 v21, v24, v26
	v_div_scale_f32 v24, s[4:5], v23, v23, v13
	v_fma_f32 v1, -v25, v21, v1
	s_cmp_eq_u32 s99, 1
	s_cbranch_scc0 .Lpf15_sp9
	s_add_i32 m0, s62, 0x12000
	s_nop 0
	global_load_lds_dwordx4 v[224:225], off
.Lpf15_sp9:
	v_rcp_f32_e32 v25, v24
	v_div_fmas_f32 v1, v1, v26, v21
	v_div_fixup_f32 v10, v1, v20, v10
	v_pk_mul_f32 v[10:11], v[14:15], v[10:11]
	v_fma_f32 v1, -v24, v25, 1.0
	v_fmac_f32_e32 v25, v1, v25
	v_div_scale_f32 v1, vcc, v13, v23, v13
	v_mul_f32_e32 v14, v1, v25
	v_fma_f32 v15, -v24, v14, v1
	v_fmac_f32_e32 v14, v15, v25
	v_div_scale_f32 v15, s[4:5], v22, v22, v12
	v_rcp_f32_e32 v20, v15
	v_fma_f32 v1, -v24, v14, v1
	v_div_fmas_f32 v1, v1, v25, v14
	v_div_fixup_f32 v13, v1, v23, v13
	v_fma_f32 v1, -v15, v20, 1.0
	v_fmac_f32_e32 v20, v1, v20
	v_div_scale_f32 v1, vcc, v12, v22, v12
	v_mul_f32_e32 v21, v1, v20
	v_fma_f32 v14, -v15, v21, v1
	v_fmac_f32_e32 v21, v14, v20
	v_fma_f32 v1, -v15, v21, v1
	v_mul_f32_e32 v14, 0xbfb8aa3b, v6
	v_mul_f32_e32 v15, 0xbfb8aa3b, v7
	v_exp_f32_e32 v14, v14
	v_exp_f32_e32 v15, v15
	v_div_fmas_f32 v1, v1, v20, v21
	v_div_fixup_f32 v12, v1, v22, v12
	v_pk_mul_f32 v[12:13], v[16:17], v[12:13]
	v_pk_add_f32 v[14:15], v[14:15], 1.0 op_sel_hi:[1,0]
	v_cvt_pk_bf16_f32 v10, v10, v11
	v_div_scale_f32 v1, s[4:5], v15, v15, v7
	v_rcp_f32_e32 v16, v1
	v_cvt_pk_bf16_f32 v11, v12, v13
	global_store_dwordx2 v[18:19], v[10:11], off
	s_add_i32 s98, s98, s10
	s_cmp_eq_u32 s99, 1
	s_cbranch_scc0 .Lpf15_sp10
	s_add_i32 m0, s62, 0x14000
	s_nop 0
	global_load_lds_dwordx4 v[226:227], off
.Lpf15_sp10:
	v_fma_f32 v10, -v1, v16, 1.0
	v_fmac_f32_e32 v16, v10, v16
	v_div_scale_f32 v10, vcc, v7, v15, v7
	v_mul_f32_e32 v11, v10, v16
	v_fma_f32 v12, -v1, v11, v10
	v_fmac_f32_e32 v11, v12, v16
	v_div_scale_f32 v12, s[4:5], v14, v14, v6
	v_rcp_f32_e32 v13, v12
	v_fma_f32 v1, -v1, v11, v10
	v_div_fmas_f32 v1, v1, v16, v11
	v_mul_f32_e32 v10, 0xbfb8aa3b, v8
	v_mul_f32_e32 v11, 0xbfb8aa3b, v9
	v_div_fixup_f32 v7, v1, v15, v7
	v_fma_f32 v1, -v12, v13, 1.0
	v_exp_f32_e32 v10, v10
	v_exp_f32_e32 v11, v11
	v_fmac_f32_e32 v13, v1, v13
	v_div_scale_f32 v1, vcc, v6, v14, v6
	v_mul_f32_e32 v15, v1, v13
	v_fma_f32 v16, -v12, v15, v1
	v_fmac_f32_e32 v15, v16, v13
	v_pk_add_f32 v[10:11], v[10:11], 1.0 op_sel_hi:[1,0]
	v_fma_f32 v1, -v12, v15, v1
	v_div_scale_f32 v12, s[4:5], v11, v11, v9
	v_rcp_f32_e32 v16, v12
	v_div_fmas_f32 v1, v1, v13, v15
	v_div_fixup_f32 v6, v1, v14, v6
	v_pk_mul_f32 v[2:3], v[2:3], v[6:7]
	v_fma_f32 v1, -v12, v16, 1.0
	v_fmac_f32_e32 v16, v1, v16
	v_div_scale_f32 v1, vcc, v9, v11, v9
	v_mul_f32_e32 v6, v1, v16
	v_fma_f32 v7, -v12, v6, v1
	v_fmac_f32_e32 v6, v7, v16
	v_fma_f32 v1, -v12, v6, v1
	v_div_scale_f32 v12, s[4:5], v10, v10, v8
	s_cmp_eq_u32 s99, 1
	s_cbranch_scc0 .Lpf15_sp11
	s_add_i32 m0, s62, 0x16000
	s_nop 0
	global_load_lds_dwordx4 v[228:229], off
.Lpf15_sp11:
	v_rcp_f32_e32 v13, v12
	v_div_fmas_f32 v1, v1, v16, v6
	v_div_fixup_f32 v7, v1, v11, v9
	s_add_i32 s38, s38, s39
	v_fma_f32 v1, -v12, v13, 1.0
	v_fmac_f32_e32 v13, v1, v13
	v_div_scale_f32 v1, vcc, v8, v10, v8
	v_mul_f32_e32 v6, v1, v13
	v_fma_f32 v9, -v12, v6, v1
	v_fmac_f32_e32 v6, v9, v13
	v_fma_f32 v1, -v12, v6, v1
	v_div_fmas_f32 v1, v1, v13, v6
	v_div_fixup_f32 v6, v1, v10, v8
	v_pk_mul_f32 v[4:5], v[4:5], v[6:7]
	v_cvt_pk_bf16_f32 v2, v2, v3
	v_cvt_pk_bf16_f32 v3, v4, v5
	s_nop 0
	global_store_dwordx2 v[18:19], v[2:3], off offset:32
	s_cmpk_lt_i32 s98, 0x800
	s_cbranch_scc1 .LBB0_1435
	v_readlane_b32 s0, v197, 18
	v_readlane_b32 s47, v196, 5
	v_readlane_b32 s96, v196, 24
	s_mov_b32 s46, s10
	v_readlane_b32 s1, v197, 19
	v_readlane_b32 s97, v196, 25
